# nt hint also on dead-after-read row loads (Y1, X/Y in second residual, XB/Y2 in final) and on the XB residual-stream stores
# baseline (speedup 1.0000x reference)
.LBB0_316:
	s_ashr_i32 s18, s9, 12
	s_ashr_i32 s5, s4, 31
	s_add_i32 s0, s4, 1
	s_mul_i32 s18, s18, 9
	s_lshl_b64 s[14:15], s[4:5], 11
	s_lshl_b64 s[16:17], s[4:5], 12
	s_ashr_i32 s1, s0, 31
	s_ashr_i32 s19, s18, 31
	v_lshl_add_u64 v[4:5], v[40:41], 0, s[14:15]
	v_lshl_add_u64 v[6:7], v[42:43], 0, s[16:17]
	s_lshl_b64 s[16:17], s[0:1], 12
	v_lshl_add_u64 v[66:67], v[44:45], 0, s[14:15]
	s_lshl_b64 s[14:15], s[18:19], 12
	s_add_u32 s5, s2, s14
	s_addc_u32 s19, s3, s15
	s_add_u32 s14, s5, 0x2000
	global_load_dwordx4 v[32:35], v[48:49], off
	global_load_dwordx2 v[86:87], v[4:5], off nt
	global_load_dwordx2 v[84:85], v[4:5], off offset:512 nt
	global_load_dwordx2 v[82:83], v[4:5], off offset:1024 nt
	global_load_dwordx2 v[80:81], v[4:5], off offset:1536 nt
	global_load_dwordx2 v[78:79], v[4:5], off offset:2048 nt
	global_load_dwordx2 v[76:77], v[4:5], off offset:2560 nt
	global_load_dwordx2 v[74:75], v[4:5], off offset:3072 nt
	global_load_dwordx2 v[72:73], v[4:5], off offset:3584 nt
	global_load_dwordx4 v[24:27], v[6:7], off nt
	global_load_dwordx4 v[16:19], v[6:7], off offset:1024 nt
	global_load_dwordx4 v[8:11], v[6:7], off offset:2048 nt
	global_load_dwordx4 v[0:3], v[6:7], off offset:3072 nt
	v_lshl_add_u64 v[36:37], v[42:43], 0, s[16:17]
	s_addc_u32 s15, s19, 0
	global_load_dwordx4 v[28:31], v[36:37], off nt
	global_load_dwordx4 v[20:23], v[36:37], off offset:1024 nt
	global_load_dwordx4 v[12:15], v[36:37], off offset:2048 nt
	global_load_dwordx4 v[4:7], v[36:37], off offset:3072 nt
	s_lshl_b64 s[0:1], s[0:1], 11
	global_load_dwordx4 v[36:39], v94, s[14:15]
	s_add_u32 s16, s5, 0x3000
	s_addc_u32 s17, s19, 0
	s_add_u32 s18, s5, 0x4000
	v_lshl_add_u64 v[68:69], v[44:45], 0, s[0:1]
	s_addc_u32 s19, s19, 0
	s_and_b32 s0, s21, 0x8000
	s_and_b32 s1, s9, 0xfffff000
	s_and_b32 s5, s4, 0xffe
	s_add_i32 s0, s0, s1
	s_or_b32 s0, s0, s5
	s_ashr_i32 s1, s0, 31
	s_lshl_b64 s[0:1], s[0:1], 11
	v_lshl_add_u64 v[70:71], v[46:47], 0, s[0:1]
	s_add_i32 s21, s21, s22
	s_add_i32 s4, s4, s23
	global_load_dwordx4 v[152:155], v95, s[14:15]
	global_load_dwordx4 v[156:159], v[50:51], off
	global_load_dwordx4 v[160:163], v96, s[14:15]
	global_load_dwordx4 v[164:167], v[52:53], off
	global_load_dwordx4 v[168:171], v97, s[14:15]
	global_load_dwordx4 v[172:175], v[54:55], off
	global_load_dwordx4 v[176:179], v94, s[18:19]
	global_load_dwordx4 v[180:183], v[56:57], off
	global_load_dwordx4 v[184:187], v94, s[16:17]
	global_load_dwordx4 v[188:191], v95, s[18:19]
	global_load_dwordx4 v[192:195], v[58:59], off
	global_load_dwordx4 v[196:199], v95, s[16:17]
	global_load_dwordx4 v[200:203], v96, s[18:19]
	global_load_dwordx4 v[204:207], v[60:61], off
	global_load_dwordx4 v[220:223], v96, s[16:17]
	global_load_dwordx4 v[224:227], v97, s[18:19]
	global_load_dwordx4 v[228:231], v[62:63], off
	global_load_dwordx4 v[232:235], v97, s[16:17]
	s_waitcnt vmcnt(34)
	v_lshlrev_b32_e32 v98, 16, v86
	v_and_b32_e32 v99, 0xffff0000, v86
	v_lshlrev_b32_e32 v86, 16, v87
	v_and_b32_e32 v87, 0xffff0000, v87
	s_waitcnt vmcnt(33)
	v_lshlrev_b32_e32 v101, 16, v85
	v_lshlrev_b32_e32 v100, 16, v84
	v_and_b32_e32 v85, 0xffff0000, v85
	v_and_b32_e32 v84, 0xffff0000, v84
	s_waitcnt vmcnt(30)
	v_lshlrev_b32_e32 v108, 16, v78
	v_and_b32_e32 v109, 0xffff0000, v78
	v_lshlrev_b32_e32 v78, 16, v79
	v_and_b32_e32 v79, 0xffff0000, v79
	s_waitcnt vmcnt(29)
	v_lshlrev_b32_e32 v111, 16, v77
	v_lshlrev_b32_e32 v110, 16, v76
	v_and_b32_e32 v77, 0xffff0000, v77
	v_and_b32_e32 v76, 0xffff0000, v76
	v_lshlrev_b32_e32 v102, 16, v82
	v_and_b32_e32 v103, 0xffff0000, v82
	v_lshlrev_b32_e32 v82, 16, v83
	v_and_b32_e32 v83, 0xffff0000, v83
	v_lshlrev_b32_e32 v105, 16, v80
	s_waitcnt vmcnt(27)
	v_lshlrev_b32_e32 v115, 16, v72
	v_mul_f32_e32 v104, v87, v87
	v_pk_mul_f32 v[118:119], v[84:85], v[84:85]
	v_mul_f32_e32 v114, v99, v99
	v_mul_f32_e32 v124, v79, v79
	v_pk_mul_f32 v[126:127], v[76:77], v[76:77]
	v_mul_f32_e32 v128, v109, v109
	v_and_b32_e32 v107, 0xffff0000, v80
	v_lshlrev_b32_e32 v112, 16, v74
	v_and_b32_e32 v113, 0xffff0000, v74
	v_lshlrev_b32_e32 v74, 16, v75
	v_and_b32_e32 v75, 0xffff0000, v75
	v_mov_b32_e32 v121, v105
	v_mul_f32_e32 v120, v103, v103
	v_mul_f32_e32 v122, v83, v83
	v_mov_b32_e32 v123, v115
	v_mov_b32_e32 v134, v100
	v_mov_b32_e32 v135, v84
	v_mov_b32_e32 v84, v101
	v_mov_b32_e32 v136, v110
	v_mov_b32_e32 v137, v76
	v_mov_b32_e32 v76, v111
	v_pk_fma_f32 v[140:141], v[86:87], v[86:87], v[104:105] op_sel_hi:[1,1,0]
	v_pk_fma_f32 v[100:101], v[100:101], v[100:101], v[118:119]
	v_pk_fma_f32 v[118:119], v[98:99], v[98:99], v[114:115] op_sel_hi:[1,1,0]
	v_pk_fma_f32 v[124:125], v[78:79], v[78:79], v[124:125] op_sel_hi:[1,1,0]
	v_pk_fma_f32 v[110:111], v[110:111], v[110:111], v[126:127]
	v_pk_fma_f32 v[126:127], v[108:109], v[108:109], v[128:129] op_sel_hi:[1,1,0]
	v_lshlrev_b32_e32 v80, 16, v81
	v_and_b32_e32 v81, 0xffff0000, v81
	v_and_b32_e32 v117, 0xffff0000, v72
	v_lshlrev_b32_e32 v72, 16, v73
	v_and_b32_e32 v73, 0xffff0000, v73
	v_mul_f32_e32 v133, v107, v107
	v_mul_f32_e32 v130, v113, v113
	v_mul_f32_e32 v132, v75, v75
	v_pk_fma_f32 v[142:143], v[102:103], v[102:103], v[120:121] op_sel_hi:[1,1,0]
	v_pk_fma_f32 v[144:145], v[82:83], v[82:83], v[122:123] op_sel_hi:[1,1,0]
	v_mov_b32_e32 v104, v118
	v_mov_b32_e32 v120, v140
	v_mov_b32_e32 v114, v126
	v_mov_b32_e32 v122, v124
	v_mul_f32_e32 v139, v80, v80
	v_mul_f32_e32 v146, v81, v81
	v_mul_f32_e32 v147, v117, v117
	v_mul_f32_e32 v148, v72, v72
	v_mul_f32_e32 v149, v73, v73
	v_mov_b32_e32 v106, v105
	v_mov_b32_e32 v116, v115
	v_pk_fma_f32 v[128:129], v[112:113], v[112:113], v[130:131] op_sel_hi:[1,1,0]
	v_pk_fma_f32 v[130:131], v[74:75], v[74:75], v[132:133] op_sel_hi:[1,1,0]
	v_pk_add_f32 v[118:119], v[118:119], v[140:141]
	v_pk_add_f32 v[100:101], v[100:101], v[100:101] op_sel:[0,1] op_sel_hi:[1,0]
	v_pk_add_f32 v[124:125], v[126:127], v[124:125]
	v_pk_add_f32 v[110:111], v[110:111], v[110:111] op_sel:[0,1] op_sel_hi:[1,0]
	v_pk_mul_f32 v[104:105], v[104:105], v[120:121]
	v_pk_mul_f32 v[114:115], v[114:115], v[122:123]
	v_mov_b32_e32 v143, v139
	v_mov_b32_e32 v145, v146
	v_mov_b32_e32 v129, v148
	v_mov_b32_e32 v131, v149
	v_mov_b32_e32 v101, v133
	v_mov_b32_e32 v111, v147
	v_mov_b32_e32 v119, v105
	v_mov_b32_e32 v125, v115
	v_pk_add_f32 v[120:121], v[142:143], v[144:145]
	v_pk_add_f32 v[122:123], v[128:129], v[130:131]
	s_waitcnt vmcnt(0)
	v_pk_mul_f32 v[34:35], v[38:39], v[34:35]
	v_pk_mul_f32 v[32:33], v[36:37], v[32:33]
	v_pk_add_f32 v[36:37], v[118:119], v[100:101]
	v_pk_add_f32 v[38:39], v[124:125], v[110:111]
	v_pk_add_f32 v[36:37], v[36:37], v[120:121]
	v_pk_add_f32 v[38:39], v[38:39], v[122:123]
	v_mov_b32_e32 v101, v36
	v_mov_b32_e32 v100, v38
	v_mov_b32_e32 v36, v39
	v_pk_add_f32 v[36:37], v[100:101], v[36:37]
	ds_bpermute_b32 v39, v88, v37
	ds_bpermute_b32 v38, v88, v36
	s_waitcnt lgkmcnt(0)
	v_pk_add_f32 v[36:37], v[36:37], v[38:39]
	ds_bpermute_b32 v39, v89, v37
	ds_bpermute_b32 v38, v89, v36
	s_waitcnt lgkmcnt(0)
	v_pk_add_f32 v[36:37], v[36:37], v[38:39]
	ds_bpermute_b32 v39, v90, v37
	ds_bpermute_b32 v38, v90, v36
	s_waitcnt lgkmcnt(0)
	v_pk_add_f32 v[36:37], v[36:37], v[38:39]
	ds_bpermute_b32 v39, v91, v37
	ds_bpermute_b32 v38, v91, v36
	s_waitcnt lgkmcnt(0)
	v_pk_add_f32 v[36:37], v[36:37], v[38:39]
	ds_bpermute_b32 v39, v92, v37
	ds_bpermute_b32 v38, v92, v36
	s_waitcnt lgkmcnt(0)
	v_pk_add_f32 v[36:37], v[36:37], v[38:39]
	ds_bpermute_b32 v39, v93, v37
	ds_bpermute_b32 v38, v93, v36
	s_waitcnt lgkmcnt(0)
	v_pk_add_f32 v[36:37], v[36:37], v[38:39]
	s_nop 0
	v_pk_fma_f32 v[36:37], v[36:37], s[8:9], v[64:65] op_sel_hi:[1,0,0]
	s_nop 0
	v_mul_f32_e32 v38, 0x4b800000, v37
	v_cmp_gt_f32_e64 s[0:1], s24, v37
	v_mul_f32_e32 v39, 0x4b800000, v36
	v_cmp_gt_f32_e32 vcc, s24, v36
	v_cndmask_b32_e64 v37, v37, v38, s[0:1]
	v_rsq_f32_e32 v37, v37
	v_cndmask_b32_e32 v36, v36, v39, vcc
	v_rsq_f32_e32 v36, v36
	v_mul_f32_e32 v38, 0x45800000, v37
	v_cndmask_b32_e64 v37, v37, v38, s[0:1]
	v_mul_f32_e32 v39, 0x45800000, v36
	v_cndmask_b32_e32 v38, v36, v39, vcc
	v_mul_f32_e32 v36, 0.5, v37
	v_mul_f32_e32 v38, 0.5, v38
	v_pk_mul_f32 v[98:99], v[36:37], v[98:99] op_sel_hi:[0,1]
	v_pk_mul_f32 v[86:87], v[36:37], v[86:87] op_sel_hi:[0,1]
	v_pk_mul_f32 v[100:101], v[38:39], v[108:109] op_sel_hi:[0,1]
	v_pk_mul_f32 v[78:79], v[38:39], v[78:79] op_sel_hi:[0,1]
	v_pk_mul_f32 v[104:105], v[36:37], v[134:135] op_sel_hi:[0,1]
	v_pk_mul_f32 v[84:85], v[36:37], v[84:85] op_sel_hi:[0,1]
	v_pk_mul_f32 v[108:109], v[38:39], v[136:137] op_sel_hi:[0,1]
	v_pk_mul_f32 v[76:77], v[38:39], v[76:77] op_sel_hi:[0,1]
	v_pk_mul_f32 v[102:103], v[36:37], v[102:103] op_sel_hi:[0,1]
	v_pk_mul_f32 v[82:83], v[36:37], v[82:83] op_sel_hi:[0,1]
	v_pk_mul_f32 v[110:111], v[38:39], v[112:113] op_sel_hi:[0,1]
	v_pk_mul_f32 v[74:75], v[38:39], v[74:75] op_sel_hi:[0,1]
	v_pk_mul_f32 v[106:107], v[36:37], v[106:107] op_sel_hi:[0,1]
	v_pk_mul_f32 v[36:37], v[36:37], v[80:81] op_sel_hi:[0,1]
	v_pk_mul_f32 v[80:81], v[38:39], v[116:117] op_sel_hi:[0,1]
	v_pk_mul_f32 v[38:39], v[38:39], v[72:73] op_sel_hi:[0,1]
	v_pk_fma_f32 v[72:73], v[34:35], v[86:87], v[26:27]
	v_pk_fma_f32 v[86:87], v[32:33], v[98:99], v[24:25]
	v_pk_fma_f32 v[34:35], v[34:35], v[78:79], v[30:31]
	v_pk_fma_f32 v[32:33], v[32:33], v[100:101], v[28:29]
	v_cvt_pk_bf16_f32 v24, v86, v87
	v_cvt_pk_bf16_f32 v25, v72, v73
	v_cvt_pk_bf16_f32 v26, v32, v33
	v_cvt_pk_bf16_f32 v27, v34, v35
	global_store_dwordx2 v[66:67], v[24:25], off nt
	global_store_dwordx2 v[68:69], v[26:27], off nt
	s_nop 0
	v_pk_mul_f32 v[78:79], v[72:73], v[72:73]
	v_pk_mul_f32 v[98:99], v[86:87], v[86:87]
	v_pk_mul_f32 v[100:101], v[34:35], v[34:35]
	v_pk_mul_f32 v[26:27], v[154:155], v[158:159]
	v_pk_mul_f32 v[24:25], v[152:153], v[156:157]
	v_pk_fma_f32 v[28:29], v[26:27], v[84:85], v[18:19]
	v_pk_fma_f32 v[30:31], v[24:25], v[104:105], v[16:17]
	v_pk_fma_f32 v[26:27], v[26:27], v[76:77], v[22:23]
	v_pk_fma_f32 v[24:25], v[24:25], v[108:109], v[20:21]
	v_cvt_pk_bf16_f32 v16, v30, v31
	v_cvt_pk_bf16_f32 v17, v28, v29
	v_cvt_pk_bf16_f32 v18, v24, v25
	v_cvt_pk_bf16_f32 v19, v26, v27
	global_store_dwordx2 v[66:67], v[16:17], off offset:512 nt
	global_store_dwordx2 v[68:69], v[18:19], off offset:512 nt
	s_nop 0
	v_pk_mul_f32 v[76:77], v[32:33], v[32:33]
	v_pk_mov_b32 v[84:85], v[98:99], v[78:79] op_sel:[1,0]
	v_mov_b32_e32 v99, v79
	v_pk_mov_b32 v[78:79], v[76:77], v[100:101] op_sel:[1,0]
	v_mov_b32_e32 v77, v101
	v_pk_add_f32 v[84:85], v[84:85], v[98:99]
	v_pk_add_f32 v[76:77], v[78:79], v[76:77]
	v_pk_add_f32 v[78:79], v[84:85], v[84:85] op_sel:[0,1] op_sel_hi:[1,0]
	v_pk_mul_f32 v[84:85], v[30:31], v[30:31]
	v_pk_mul_f32 v[98:99], v[26:27], v[26:27]
	v_pk_add_f32 v[76:77], v[76:77], v[76:77] op_sel:[0,1] op_sel_hi:[1,0]
	v_pk_mul_f32 v[18:19], v[162:163], v[166:167]
	v_pk_mul_f32 v[16:17], v[160:161], v[164:165]
	v_pk_fma_f32 v[20:21], v[82:83], v[18:19], v[10:11]
	v_pk_fma_f32 v[22:23], v[102:103], v[16:17], v[8:9]
	v_pk_fma_f32 v[18:19], v[18:19], v[74:75], v[14:15]
	v_pk_fma_f32 v[16:17], v[16:17], v[110:111], v[12:13]
	v_cvt_pk_bf16_f32 v8, v22, v23
	v_cvt_pk_bf16_f32 v9, v20, v21
	v_cvt_pk_bf16_f32 v10, v16, v17
	v_cvt_pk_bf16_f32 v11, v18, v19
	global_store_dwordx2 v[66:67], v[8:9], off offset:1024 nt
	global_store_dwordx2 v[68:69], v[10:11], off offset:1024 nt
	s_nop 0
	v_pk_mul_f32 v[74:75], v[28:29], v[28:29]
	v_pk_mul_f32 v[82:83], v[24:25], v[24:25]
	v_pk_mov_b32 v[100:101], v[84:85], v[74:75] op_sel:[1,0]
	v_mov_b32_e32 v85, v75
	v_pk_mov_b32 v[74:75], v[82:83], v[98:99] op_sel:[1,0]
	v_mov_b32_e32 v83, v99
	v_pk_add_f32 v[84:85], v[100:101], v[84:85]
	v_pk_add_f32 v[74:75], v[74:75], v[82:83]
	v_pk_add_f32 v[82:83], v[84:85], v[84:85] op_sel:[0,1] op_sel_hi:[1,0]
	v_mul_f32_e32 v84, v23, v23
	v_mul_f32_e32 v98, v21, v21
	v_mul_f32_e32 v100, v17, v17
	v_mul_f32_e32 v102, v19, v19
	v_pk_add_f32 v[74:75], v[74:75], v[74:75] op_sel:[0,1] op_sel_hi:[1,0]
	v_pk_fma_f32 v[84:85], v[22:23], v[22:23], v[84:85] op_sel_hi:[1,1,0]
	v_pk_fma_f32 v[98:99], v[20:21], v[20:21], v[98:99] op_sel_hi:[1,1,0]
	v_pk_fma_f32 v[100:101], v[16:17], v[16:17], v[100:101] op_sel_hi:[1,1,0]
	v_pk_fma_f32 v[102:103], v[18:19], v[18:19], v[102:103] op_sel_hi:[1,1,0]
	v_pk_mul_f32 v[10:11], v[170:171], v[174:175]
	v_pk_mul_f32 v[8:9], v[168:169], v[172:173]
	v_pk_fma_f32 v[12:13], v[36:37], v[10:11], v[2:3]
	v_pk_fma_f32 v[14:15], v[106:107], v[8:9], v[0:1]
	v_pk_fma_f32 v[36:37], v[38:39], v[10:11], v[6:7]
	v_pk_fma_f32 v[38:39], v[80:81], v[8:9], v[4:5]
	v_cvt_pk_bf16_f32 v0, v14, v15
	v_cvt_pk_bf16_f32 v1, v12, v13
	v_cvt_pk_bf16_f32 v2, v38, v39
	v_cvt_pk_bf16_f32 v3, v36, v37
	global_store_dwordx2 v[66:67], v[0:1], off offset:1536 nt
	global_store_dwordx2 v[68:69], v[2:3], off offset:1536 nt
	s_nop 0
	v_mul_f32_e32 v79, v14, v14
	v_mul_f32_e32 v83, v15, v15
	v_mul_f32_e32 v85, v12, v12
	v_mul_f32_e32 v99, v13, v13
	v_mul_f32_e32 v101, v38, v38
	v_mul_f32_e32 v103, v39, v39
	v_mul_f32_e32 v77, v36, v36
	v_mul_f32_e32 v75, v37, v37
	v_pk_add_f32 v[66:67], v[78:79], v[82:83]
	v_pk_add_f32 v[68:69], v[84:85], v[98:99]
	v_pk_add_f32 v[78:79], v[100:101], v[102:103]
	v_pk_add_f32 v[74:75], v[76:77], v[74:75]
	v_pk_add_f32 v[66:67], v[66:67], v[68:69]
	v_pk_add_f32 v[68:69], v[78:79], v[74:75]
	v_mov_b32_e32 v75, v66
	v_mov_b32_e32 v74, v68
	v_mov_b32_e32 v66, v69
	v_pk_add_f32 v[66:67], v[74:75], v[66:67]
	ds_bpermute_b32 v69, v88, v67
	ds_bpermute_b32 v68, v88, v66
	s_waitcnt lgkmcnt(0)
	v_pk_add_f32 v[66:67], v[66:67], v[68:69]
	ds_bpermute_b32 v69, v89, v67
	ds_bpermute_b32 v68, v89, v66
	s_waitcnt lgkmcnt(0)
	v_pk_add_f32 v[66:67], v[66:67], v[68:69]
	ds_bpermute_b32 v69, v90, v67
	ds_bpermute_b32 v68, v90, v66
	s_waitcnt lgkmcnt(0)
	v_pk_add_f32 v[66:67], v[66:67], v[68:69]
	ds_bpermute_b32 v69, v91, v67
	ds_bpermute_b32 v68, v91, v66
	s_waitcnt lgkmcnt(0)
	v_pk_add_f32 v[66:67], v[66:67], v[68:69]
	ds_bpermute_b32 v69, v92, v67
	ds_bpermute_b32 v68, v92, v66
	s_waitcnt lgkmcnt(0)
	v_pk_add_f32 v[66:67], v[66:67], v[68:69]
	ds_bpermute_b32 v69, v93, v67
	ds_bpermute_b32 v68, v93, v66
	s_waitcnt lgkmcnt(0)
	v_pk_add_f32 v[66:67], v[66:67], v[68:69]
	s_nop 0
	v_pk_fma_f32 v[66:67], v[66:67], s[8:9], v[64:65] op_sel_hi:[1,0,0]
	s_add_i32 s9, s9, s20
	v_mul_f32_e32 v68, 0x4b800000, v67
	v_cmp_gt_f32_e64 s[0:1], s24, v67
	v_mul_f32_e32 v69, 0x4b800000, v66
	v_cmp_gt_f32_e32 vcc, s24, v66
	v_cndmask_b32_e64 v67, v67, v68, s[0:1]
	v_rsq_f32_e32 v67, v67
	v_cndmask_b32_e32 v66, v66, v69, vcc
	v_rsq_f32_e32 v68, v66
	s_cmp_lt_i32 s9, 0x8000
	v_mul_f32_e32 v66, 0x45800000, v67
	v_cndmask_b32_e64 v66, v67, v66, s[0:1]
	v_mul_f32_e32 v69, 0x45800000, v68
	v_cndmask_b32_e32 v68, v68, v69, vcc
	v_pk_mul_f32 v[74:75], v[86:87], v[66:67] op_sel_hi:[1,0]
	v_pk_mul_f32 v[72:73], v[72:73], v[66:67] op_sel_hi:[1,0]
	v_pk_add_f32 v[2:3], v[178:179], 1.0 op_sel_hi:[1,0]
	v_pk_add_f32 v[0:1], v[176:177], 1.0 op_sel_hi:[1,0]
	v_pk_mul_f32 v[2:3], v[182:183], v[2:3]
	v_pk_mul_f32 v[0:1], v[180:181], v[0:1]
	v_pk_mul_f32 v[32:33], v[32:33], v[68:69] op_sel_hi:[1,0]
	v_pk_mul_f32 v[34:35], v[34:35], v[68:69] op_sel_hi:[1,0]
	v_pk_fma_f32 v[4:5], v[2:3], v[72:73], v[186:187]
	v_pk_fma_f32 v[6:7], v[0:1], v[74:75], v[184:185]
	v_pk_fma_f32 v[2:3], v[2:3], v[34:35], v[186:187]
	v_pk_fma_f32 v[0:1], v[0:1], v[32:33], v[184:185]
	v_cvt_pk_bf16_f32 v6, v6, v7
	v_cvt_pk_bf16_f32 v7, v4, v5
	v_cvt_pk_bf16_f32 v0, v0, v1
	v_cvt_pk_bf16_f32 v1, v2, v3
	global_store_dwordx2 v[70:71], v[6:7], off
	global_store_dwordx2 v[70:71], v[0:1], off offset:2048
	s_nop 0
	v_pk_mul_f32 v[30:31], v[30:31], v[66:67] op_sel_hi:[1,0]
	v_pk_mul_f32 v[28:29], v[28:29], v[66:67] op_sel_hi:[1,0]
	v_pk_mul_f32 v[24:25], v[24:25], v[68:69] op_sel_hi:[1,0]
	v_pk_mul_f32 v[26:27], v[26:27], v[68:69] op_sel_hi:[1,0]
	v_pk_mul_f32 v[22:23], v[22:23], v[66:67] op_sel_hi:[1,0]
	v_pk_mul_f32 v[20:21], v[20:21], v[66:67] op_sel_hi:[1,0]
	v_pk_mul_f32 v[16:17], v[16:17], v[68:69] op_sel_hi:[1,0]
	v_pk_mul_f32 v[18:19], v[18:19], v[68:69] op_sel_hi:[1,0]
	v_pk_mul_f32 v[14:15], v[14:15], v[66:67] op_sel_hi:[1,0]
	v_pk_mul_f32 v[12:13], v[12:13], v[66:67] op_sel_hi:[1,0]
	v_pk_add_f32 v[2:3], v[190:191], 1.0 op_sel_hi:[1,0]
	v_pk_add_f32 v[0:1], v[188:189], 1.0 op_sel_hi:[1,0]
	v_pk_mul_f32 v[2:3], v[194:195], v[2:3]
	v_pk_mul_f32 v[0:1], v[192:193], v[0:1]
	v_pk_fma_f32 v[4:5], v[2:3], v[28:29], v[198:199]
	v_pk_fma_f32 v[6:7], v[0:1], v[30:31], v[196:197]
	v_pk_fma_f32 v[2:3], v[2:3], v[26:27], v[198:199]
	v_pk_fma_f32 v[0:1], v[0:1], v[24:25], v[196:197]
	v_cvt_pk_bf16_f32 v6, v6, v7
	v_cvt_pk_bf16_f32 v7, v4, v5
	v_cvt_pk_bf16_f32 v0, v0, v1
	v_cvt_pk_bf16_f32 v1, v2, v3
	global_store_dwordx2 v[70:71], v[6:7], off offset:512
	global_store_dwordx2 v[70:71], v[0:1], off offset:2560
	s_nop 0
	v_pk_add_f32 v[2:3], v[202:203], 1.0 op_sel_hi:[1,0]
	v_pk_add_f32 v[0:1], v[200:201], 1.0 op_sel_hi:[1,0]
	v_pk_mul_f32 v[2:3], v[206:207], v[2:3]
	v_pk_mul_f32 v[0:1], v[204:205], v[0:1]
	v_pk_fma_f32 v[4:5], v[20:21], v[2:3], v[222:223]
	v_pk_fma_f32 v[6:7], v[22:23], v[0:1], v[220:221]
	v_pk_fma_f32 v[2:3], v[18:19], v[2:3], v[222:223]
	v_pk_fma_f32 v[0:1], v[16:17], v[0:1], v[220:221]
	v_cvt_pk_bf16_f32 v6, v6, v7
	v_cvt_pk_bf16_f32 v7, v4, v5
	v_cvt_pk_bf16_f32 v0, v0, v1
	v_cvt_pk_bf16_f32 v1, v2, v3
	global_store_dwordx2 v[70:71], v[6:7], off offset:1024
	global_store_dwordx2 v[70:71], v[0:1], off offset:3072
	s_nop 0
	v_pk_mul_f32 v[16:17], v[38:39], v[68:69] op_sel_hi:[1,0]
	v_pk_mul_f32 v[18:19], v[36:37], v[68:69] op_sel_hi:[1,0]
	v_pk_add_f32 v[2:3], v[226:227], 1.0 op_sel_hi:[1,0]
	v_pk_add_f32 v[0:1], v[224:225], 1.0 op_sel_hi:[1,0]
	v_pk_mul_f32 v[2:3], v[230:231], v[2:3]
	v_pk_mul_f32 v[0:1], v[228:229], v[0:1]
	v_pk_fma_f32 v[4:5], v[12:13], v[2:3], v[234:235]
	v_pk_fma_f32 v[6:7], v[14:15], v[0:1], v[232:233]
	v_pk_fma_f32 v[2:3], v[18:19], v[2:3], v[234:235]
	v_pk_fma_f32 v[0:1], v[16:17], v[0:1], v[232:233]
	v_cvt_pk_bf16_f32 v6, v6, v7
	v_cvt_pk_bf16_f32 v7, v4, v5
	v_cvt_pk_bf16_f32 v0, v0, v1
	v_cvt_pk_bf16_f32 v1, v2, v3
	global_store_dwordx2 v[70:71], v[6:7], off offset:1536
	global_store_dwordx2 v[70:71], v[0:1], off offset:3584
	s_cbranch_scc1 .LBB0_316

.LBB0_912:
	s_ashr_i32 s98, s2, 11
	s_mul_i32 s98, s98, 9
	s_ashr_i32 s99, s98, 31
	s_lshl_b64 s[98:99], s[98:99], 12
	s_add_u32 s98, s14, s98
	s_addc_u32 s99, s15, s99
	s_add_u32 s98, s98, 0x5000
	s_addc_u32 s99, s99, 0
	s_and_b32 s0, s18, 0x8000
	s_and_b32 s1, s7, 0xfffff000
	s_add_i32 s0, s0, s1
	s_and_b32 s1, s4, 0xffc
	s_or_b32 s0, s0, s1
	s_ashr_i32 s1, s0, 31
	s_lshl_b64 s[0:1], s[0:1], 11
	s_ashr_i32 s5, s4, 31
	v_lshl_add_u64 v[64:65], v[4:5], 0, s[0:1]
	s_lshl_b64 s[10:11], s[4:5], 11
	v_lshl_add_u64 v[0:1], v[6:7], 0, s[10:11]
	global_load_dwordx2 v[80:81], v[64:65], off nt
	global_load_dwordx2 v[2:3], v[0:1], off nt
	s_add_i32 s0, s4, 1
	s_ashr_i32 s1, s0, 31
	s_lshl_b64 s[0:1], s[0:1], 11
	v_lshl_add_u64 v[40:41], v[6:7], 0, s[0:1]
	s_add_i32 s0, s4, 2
	s_ashr_i32 s1, s0, 31
	s_lshl_b64 s[0:1], s[0:1], 11
	v_lshl_add_u64 v[88:89], v[6:7], 0, s[0:1]
	s_movk_i32 s0, 0x1000
	v_add_co_u32_e32 v90, vcc, s0, v64
	s_add_i32 s0, s4, 3
	s_nop 0
	v_addc_co_u32_e32 v91, vcc, 0, v65, vcc
	s_ashr_i32 s1, s0, 31
	s_lshl_b64 s[0:1], s[0:1], 11
	v_lshl_add_u64 v[106:107], v[6:7], 0, s[0:1]
	s_mov_b32 s17, s11
	global_load_dwordx2 v[82:83], v[64:65], off offset:512 nt
	global_load_dwordx2 v[202:203], v[0:1], off offset:512 nt
	global_load_dwordx2 v[84:85], v[64:65], off offset:1024 nt
	global_load_dwordx2 v[204:205], v[0:1], off offset:1024 nt
	global_load_dwordx2 v[86:87], v[64:65], off offset:1536 nt
	global_load_dwordx2 v[32:33], v[0:1], off offset:1536 nt
	global_load_dwordx2 v[96:97], v[64:65], off offset:2048 nt
	global_load_dwordx2 v[44:45], v[40:41], off nt
	global_load_dwordx2 v[126:127], v[64:65], off offset:2560 nt
	global_load_dwordx2 v[206:207], v[40:41], off offset:512 nt
	global_load_dwordx2 v[128:129], v[64:65], off offset:3072 nt
	global_load_dwordx2 v[220:221], v[40:41], off offset:1024 nt
	global_load_dwordx2 v[140:141], v[64:65], off offset:3584 nt
	global_load_dwordx2 v[46:47], v[40:41], off offset:1536 nt
	global_load_dwordx2 v[98:99], v[90:91], off nt
	global_load_dwordx2 v[64:65], v[88:89], off nt
	global_load_dwordx2 v[100:101], v[90:91], off offset:512 nt
	global_load_dwordx2 v[222:223], v[88:89], off offset:512 nt
	global_load_dwordx2 v[142:143], v[90:91], off offset:1024 nt
	global_load_dwordx2 v[224:225], v[88:89], off offset:1024 nt
	global_load_dwordx2 v[148:149], v[90:91], off offset:1536 nt
	global_load_dwordx2 v[76:77], v[88:89], off offset:1536 nt
	global_load_dwordx2 v[150:151], v[90:91], off offset:2048 nt
	global_load_dwordx2 v[78:79], v[106:107], off nt
	global_load_dwordx2 v[152:153], v[90:91], off offset:2560 nt
	global_load_dwordx2 v[92:93], v[106:107], off offset:512 nt
	global_load_dwordx2 v[160:161], v[90:91], off offset:3072 nt
	global_load_dwordx2 v[226:227], v[106:107], off offset:1024 nt
	global_load_dwordx2 v[174:175], v[90:91], off offset:3584 nt
	global_load_dwordx2 v[90:91], v[106:107], off offset:1536 nt
	global_load_dwordx4 v[228:231], v190, s[98:99]
	global_load_dwordx4 v[198:201], v[10:11], off
	global_load_dwordx4 v[232:235], v191, s[98:99]
	global_load_dwordx4 v[236:239], v[12:13], off
	global_load_dwordx4 v[240:243], v192, s[98:99]
	global_load_dwordx4 v[244:247], v[14:15], off
	global_load_dwordx4 v[212:215], v193, s[98:99]
	global_load_dwordx4 v[216:219], v[16:17], off
	s_waitcnt vmcnt(0)
	v_lshlrev_b32_e32 v48, 16, v2
	v_and_b32_e32 v49, 0xffff0000, v2
	v_lshlrev_b32_e32 v50, 16, v3
	v_and_b32_e32 v51, 0xffff0000, v3
	v_lshlrev_b32_e32 v38, 16, v202
	v_and_b32_e32 v39, 0xffff0000, v202
	v_lshlrev_b32_e32 v42, 16, v203
	v_and_b32_e32 v43, 0xffff0000, v203
	v_lshlrev_b32_e32 v132, 16, v84
	v_and_b32_e32 v133, 0xffff0000, v84
	v_lshlrev_b32_e32 v134, 16, v85
	v_lshlrev_b32_e32 v60, 16, v44
	v_and_b32_e32 v61, 0xffff0000, v44
	v_lshlrev_b32_e32 v62, 16, v45
	v_and_b32_e32 v63, 0xffff0000, v45
	v_and_b32_e32 v135, 0xffff0000, v85
	v_lshlrev_b32_e32 v121, 16, v86
	v_and_b32_e32 v119, 0xffff0000, v86
	v_mul_f32_e32 v118, v119, v119
	v_lshlrev_b32_e32 v34, 16, v204
	v_and_b32_e32 v35, 0xffff0000, v204
	v_lshlrev_b32_e32 v36, 16, v205
	v_and_b32_e32 v37, 0xffff0000, v205
	v_lshlrev_b32_e32 v2, 16, v32
	v_and_b32_e32 v3, 0xffff0000, v32
	v_lshlrev_b32_e32 v32, 16, v33
	v_and_b32_e32 v33, 0xffff0000, v33
	v_lshlrev_b32_e32 v56, 16, v206
	v_and_b32_e32 v57, 0xffff0000, v206
	v_lshlrev_b32_e32 v58, 16, v207
	v_and_b32_e32 v59, 0xffff0000, v207
	s_nop 0
	v_lshlrev_b32_e32 v138, 16, v129
	v_and_b32_e32 v139, 0xffff0000, v129
	v_and_b32_e32 v129, 0xffff0000, v140
	v_lshlrev_b32_e32 v72, 16, v64
	v_and_b32_e32 v73, 0xffff0000, v64
	v_lshlrev_b32_e32 v74, 16, v65
	v_and_b32_e32 v75, 0xffff0000, v65
	v_lshlrev_b32_e32 v176, 16, v98
	v_and_b32_e32 v177, 0xffff0000, v98
	v_lshlrev_b32_e32 v98, 16, v99
	v_and_b32_e32 v99, 0xffff0000, v99
	v_lshlrev_b32_e32 v52, 16, v220
	v_and_b32_e32 v53, 0xffff0000, v220
	v_lshlrev_b32_e32 v54, 16, v221
	v_and_b32_e32 v55, 0xffff0000, v221
	v_lshlrev_b32_e32 v44, 16, v46
	v_and_b32_e32 v45, 0xffff0000, v46
	v_lshlrev_b32_e32 v46, 16, v47
	v_and_b32_e32 v47, 0xffff0000, v47
	v_and_b32_e32 v165, 0xffff0000, v101
	v_lshlrev_b32_e32 v66, 16, v222
	v_and_b32_e32 v67, 0xffff0000, v222
	v_lshlrev_b32_e32 v68, 16, v223
	v_and_b32_e32 v69, 0xffff0000, v223
	v_and_b32_e32 v164, 0xffff0000, v100
	v_lshlrev_b32_e32 v163, 16, v101
	v_lshlrev_b32_e32 v162, 16, v100
	v_pk_mul_f32 v[100:101], v[164:165], v[164:165]
	v_lshlrev_b32_e32 v70, 16, v224
	v_pk_fma_f32 v[100:101], v[162:163], v[162:163], v[100:101]
	v_and_b32_e32 v181, 0xffff0000, v151
	v_lshlrev_b32_e32 v122, 16, v92
	v_and_b32_e32 v123, 0xffff0000, v92
	v_lshlrev_b32_e32 v124, 16, v93
	v_and_b32_e32 v125, 0xffff0000, v93
	s_nop 0
	v_pk_add_f32 v[100:101], v[100:101], v[100:101] op_sel:[0,1] op_sel_hi:[1,0]
	v_and_b32_e32 v179, 0xffff0000, v150
	v_lshlrev_b32_e32 v180, 16, v151
	v_and_b32_e32 v173, 0xffff0000, v153
	v_lshlrev_b32_e32 v178, 16, v150
	v_lshlrev_b32_e32 v102, 16, v76
	v_and_b32_e32 v103, 0xffff0000, v76
	v_lshlrev_b32_e32 v104, 16, v77
	v_and_b32_e32 v105, 0xffff0000, v77
	v_lshlrev_b32_e32 v76, 16, v78
	v_and_b32_e32 v77, 0xffff0000, v78
	v_lshlrev_b32_e32 v78, 16, v79
	v_and_b32_e32 v79, 0xffff0000, v79
	v_and_b32_e32 v71, 0xffff0000, v224
	v_lshlrev_b32_e32 v64, 16, v225
	v_and_b32_e32 v65, 0xffff0000, v225
	v_and_b32_e32 v151, 0xffff0000, v174
	v_lshlrev_b32_e32 v114, 16, v227
	v_and_b32_e32 v115, 0xffff0000, v227
	v_and_b32_e32 v93, 0xffff0000, v81
	v_lshlrev_b32_e32 v112, 16, v226
	v_and_b32_e32 v113, 0xffff0000, v226
	v_lshlrev_b32_e32 v108, 16, v90
	v_and_b32_e32 v109, 0xffff0000, v90
	v_lshlrev_b32_e32 v110, 16, v91
	v_and_b32_e32 v111, 0xffff0000, v91
	v_lshlrev_b32_e32 v90, 16, v80
	v_and_b32_e32 v91, 0xffff0000, v80
	v_lshlrev_b32_e32 v92, 16, v81
	v_mul_f32_e32 v80, v93, v93
	v_pk_fma_f32 v[94:95], v[92:93], v[92:93], v[80:81] op_sel_hi:[1,1,0]
	v_lshlrev_b32_e32 v81, 16, v83
	v_lshlrev_b32_e32 v80, 16, v82
	v_and_b32_e32 v83, 0xffff0000, v83
	v_and_b32_e32 v82, 0xffff0000, v82
	v_mul_f32_e32 v84, v91, v91
	v_pk_mul_f32 v[116:117], v[82:83], v[82:83]
	v_pk_fma_f32 v[84:85], v[90:91], v[90:91], v[84:85] op_sel_hi:[1,1,0]
	v_pk_fma_f32 v[130:131], v[80:81], v[80:81], v[116:117]
	v_lshlrev_b32_e32 v116, 16, v87
	v_and_b32_e32 v117, 0xffff0000, v87
	v_mov_b32_e32 v120, v84
	v_mov_b32_e32 v86, v94
	v_mov_b32_e32 v87, v121
	v_pk_add_f32 v[84:85], v[84:85], v[94:95]
	v_pk_mul_f32 v[86:87], v[120:121], v[86:87]
	v_mul_f32_e32 v94, v135, v135
	v_mov_b32_e32 v85, v87
	v_pk_add_f32 v[86:87], v[130:131], v[130:131] op_sel:[0,1] op_sel_hi:[1,0]
	v_mul_f32_e32 v136, v116, v116
	v_mov_b32_e32 v87, v118
	v_pk_add_f32 v[84:85], v[84:85], v[86:87]
	v_mul_f32_e32 v86, v133, v133
	v_mul_f32_e32 v137, v117, v117
	v_pk_fma_f32 v[86:87], v[132:133], v[132:133], v[86:87] op_sel_hi:[1,1,0]
	v_pk_fma_f32 v[94:95], v[134:135], v[134:135], v[94:95] op_sel_hi:[1,1,0]
	v_mov_b32_e32 v87, v136
	v_mov_b32_e32 v95, v137
	v_pk_add_f32 v[86:87], v[86:87], v[94:95]
	v_lshlrev_b32_e32 v94, 16, v96
	v_and_b32_e32 v95, 0xffff0000, v96
	v_lshlrev_b32_e32 v96, 16, v97
	v_and_b32_e32 v97, 0xffff0000, v97
	v_pk_add_f32 v[144:145], v[84:85], v[86:87]
	v_mul_f32_e32 v84, v97, v97
	v_and_b32_e32 v87, 0xffff0000, v127
	v_and_b32_e32 v86, 0xffff0000, v126
	v_pk_fma_f32 v[146:147], v[96:97], v[96:97], v[84:85] op_sel_hi:[1,1,0]
	v_lshlrev_b32_e32 v85, 16, v127
	v_lshlrev_b32_e32 v84, 16, v126
	v_pk_mul_f32 v[126:127], v[86:87], v[86:87]
	v_mul_f32_e32 v118, v95, v95
	v_pk_fma_f32 v[154:155], v[84:85], v[84:85], v[126:127]
	v_lshlrev_b32_e32 v131, 16, v140
	v_lshlrev_b32_e32 v126, 16, v141
	v_and_b32_e32 v127, 0xffff0000, v141
	v_pk_fma_f32 v[140:141], v[94:95], v[94:95], v[118:119] op_sel_hi:[1,1,0]
	v_mov_b32_e32 v156, v146
	v_mov_b32_e32 v130, v140
	v_mov_b32_e32 v157, v131
	v_pk_add_f32 v[140:141], v[140:141], v[146:147]
	v_pk_mul_f32 v[146:147], v[130:131], v[156:157]
	v_and_b32_e32 v137, 0xffff0000, v128
	v_mul_f32_e32 v120, v129, v129
	v_mov_b32_e32 v141, v147
	v_pk_add_f32 v[146:147], v[154:155], v[154:155] op_sel:[0,1] op_sel_hi:[1,0]
	v_lshlrev_b32_e32 v136, 16, v128
	v_mov_b32_e32 v147, v120
	v_mul_f32_e32 v118, v137, v137
	v_pk_add_f32 v[140:141], v[140:141], v[146:147]
	v_pk_fma_f32 v[146:147], v[136:137], v[136:137], v[118:119] op_sel_hi:[1,1,0]
	v_mul_f32_e32 v118, v139, v139
	v_mul_f32_e32 v128, v126, v126
	v_mul_f32_e32 v158, v127, v127
	v_pk_fma_f32 v[154:155], v[138:139], v[138:139], v[118:119] op_sel_hi:[1,1,0]
	v_mov_b32_e32 v147, v128
	v_mov_b32_e32 v155, v158
	v_pk_add_f32 v[146:147], v[146:147], v[154:155]
	v_lshlrev_b32_e32 v154, 16, v142
	v_pk_add_f32 v[140:141], v[140:141], v[146:147]
	v_mov_b32_e32 v147, v144
	v_mov_b32_e32 v146, v140
	v_mov_b32_e32 v144, v141
	v_pk_add_f32 v[140:141], v[146:147], v[144:145]
	ds_bpermute_b32 v145, v184, v141
	ds_bpermute_b32 v144, v184, v140
	v_and_b32_e32 v155, 0xffff0000, v142
	v_lshlrev_b32_e32 v156, 16, v143
	v_and_b32_e32 v157, 0xffff0000, v143
	v_lshlrev_b32_e32 v147, 16, v148
	s_waitcnt lgkmcnt(0)
	v_pk_add_f32 v[140:141], v[140:141], v[144:145]
	ds_bpermute_b32 v145, v185, v141
	ds_bpermute_b32 v144, v185, v140
	v_lshlrev_b32_e32 v142, 16, v149
	v_and_b32_e32 v143, 0xffff0000, v149
	v_mov_b32_e32 v167, v147
	v_mul_f32_e32 v172, v143, v143
	s_waitcnt lgkmcnt(0)
	v_pk_add_f32 v[140:141], v[140:141], v[144:145]
	ds_bpermute_b32 v145, v186, v141
	ds_bpermute_b32 v144, v186, v140
	s_waitcnt lgkmcnt(0)
	v_pk_add_f32 v[140:141], v[140:141], v[144:145]
	ds_bpermute_b32 v145, v187, v141
	ds_bpermute_b32 v144, v187, v140
	s_waitcnt lgkmcnt(0)
	v_pk_add_f32 v[140:141], v[140:141], v[144:145]
	ds_bpermute_b32 v145, v188, v141
	ds_bpermute_b32 v144, v188, v140
	s_waitcnt lgkmcnt(0)
	v_pk_add_f32 v[140:141], v[140:141], v[144:145]
	ds_bpermute_b32 v145, v189, v141
	ds_bpermute_b32 v144, v189, v140
	s_waitcnt lgkmcnt(0)
	v_pk_add_f32 v[144:145], v[140:141], v[144:145]
	v_mov_b64_e32 v[140:141], s[8:9]
	v_pk_fma_f32 v[144:145], v[144:145], s[6:7], v[140:141] op_sel_hi:[1,0,0]
	s_nop 0
	v_mul_f32_e32 v118, 0x4b800000, v145
	v_cmp_gt_f32_e64 s[0:1], s21, v145
	v_cmp_gt_f32_e32 vcc, s21, v144
	s_nop 0
	v_cndmask_b32_e64 v118, v145, v118, s[0:1]
	v_rsq_f32_e32 v118, v118
	v_and_b32_e32 v145, 0xffff0000, v148
	v_mul_f32_e32 v130, v145, v145
	v_mov_b32_e32 v101, v130
	v_mul_f32_e32 v120, 0x45800000, v118
	v_cndmask_b32_e64 v128, v118, v120, s[0:1]
	v_mul_f32_e32 v118, 0x4b800000, v144
	v_cndmask_b32_e32 v118, v144, v118, vcc
	v_rsq_f32_e32 v118, v118
	v_mul_f32_e32 v144, v142, v142
	v_mul_f32_e32 v130, v151, v151
	v_pk_mul_f32 v[90:91], v[128:129], v[90:91] op_sel_hi:[0,1]
	v_mul_f32_e32 v120, 0x45800000, v118
	v_cndmask_b32_e32 v120, v118, v120, vcc
	v_mul_f32_e32 v118, v99, v99
	v_pk_fma_f32 v[158:159], v[98:99], v[98:99], v[118:119] op_sel_hi:[1,1,0]
	v_mul_f32_e32 v118, v177, v177
	v_pk_fma_f32 v[148:149], v[176:177], v[176:177], v[118:119] op_sel_hi:[1,1,0]
	v_mov_b32_e32 v166, v158
	v_mov_b32_e32 v146, v148
	v_pk_add_f32 v[148:149], v[148:149], v[158:159]
	v_pk_mul_f32 v[158:159], v[146:147], v[166:167]
	v_mul_f32_e32 v118, v155, v155
	v_mov_b32_e32 v149, v159
	v_pk_add_f32 v[100:101], v[148:149], v[100:101]
	v_pk_fma_f32 v[148:149], v[154:155], v[154:155], v[118:119] op_sel_hi:[1,1,0]
	v_mul_f32_e32 v118, v157, v157
	v_pk_fma_f32 v[158:159], v[156:157], v[156:157], v[118:119] op_sel_hi:[1,1,0]
	v_mov_b32_e32 v149, v144
	v_mov_b32_e32 v159, v172
	v_pk_add_f32 v[148:149], v[148:149], v[158:159]
	v_mul_f32_e32 v118, v181, v181
	v_and_b32_e32 v172, 0xffff0000, v152
	v_pk_add_f32 v[100:101], v[100:101], v[148:149]
	v_pk_fma_f32 v[182:183], v[180:181], v[180:181], v[118:119] op_sel_hi:[1,1,0]
	v_lshlrev_b32_e32 v167, 16, v153
	v_lshlrev_b32_e32 v166, 16, v152
	v_pk_mul_f32 v[148:149], v[172:173], v[172:173]
	v_mul_f32_e32 v118, v179, v179
	v_pk_fma_f32 v[194:195], v[166:167], v[166:167], v[148:149]
	v_lshlrev_b32_e32 v153, 16, v174
	v_lshlrev_b32_e32 v148, 16, v175
	v_and_b32_e32 v149, 0xffff0000, v175
	v_pk_fma_f32 v[174:175], v[178:179], v[178:179], v[118:119] op_sel_hi:[1,1,0]
	v_mov_b32_e32 v196, v182
	v_mov_b32_e32 v152, v174
	v_mov_b32_e32 v197, v153
	v_pk_add_f32 v[174:175], v[174:175], v[182:183]
	v_pk_mul_f32 v[182:183], v[152:153], v[196:197]
	v_and_b32_e32 v159, 0xffff0000, v160
	v_mov_b32_e32 v175, v183
	v_pk_add_f32 v[182:183], v[194:195], v[194:195] op_sel:[0,1] op_sel_hi:[1,0]
	v_lshlrev_b32_e32 v158, 16, v160
	v_lshlrev_b32_e32 v160, 16, v161
	v_and_b32_e32 v161, 0xffff0000, v161
	v_mov_b32_e32 v183, v130
	v_mul_f32_e32 v118, v159, v159
	v_pk_add_f32 v[174:175], v[174:175], v[182:183]
	v_pk_fma_f32 v[182:183], v[158:159], v[158:159], v[118:119] op_sel_hi:[1,1,0]
	v_mul_f32_e32 v118, v161, v161
	v_mul_f32_e32 v144, v148, v148
	v_mul_f32_e32 v146, v149, v149
	v_pk_fma_f32 v[194:195], v[160:161], v[160:161], v[118:119] op_sel_hi:[1,1,0]
	v_mov_b32_e32 v183, v144
	v_mov_b32_e32 v195, v146
	v_pk_add_f32 v[182:183], v[182:183], v[194:195]
	v_pk_mul_f32 v[92:93], v[128:129], v[92:93] op_sel_hi:[0,1]
	v_pk_add_f32 v[174:175], v[174:175], v[182:183]
	v_mov_b32_e32 v183, v100
	v_mov_b32_e32 v182, v174
	v_mov_b32_e32 v100, v175
	v_pk_add_f32 v[100:101], v[182:183], v[100:101]
	ds_bpermute_b32 v175, v184, v101
	ds_bpermute_b32 v174, v184, v100
	v_mov_b32_e32 v144, v147
	v_mov_b32_e32 v150, v153
	s_waitcnt lgkmcnt(0)
	v_pk_add_f32 v[100:101], v[100:101], v[174:175]
	ds_bpermute_b32 v175, v185, v101
	ds_bpermute_b32 v174, v185, v100
	s_waitcnt lgkmcnt(0)
	v_pk_add_f32 v[100:101], v[100:101], v[174:175]
	ds_bpermute_b32 v175, v186, v101
	ds_bpermute_b32 v174, v186, v100
	s_waitcnt lgkmcnt(0)
	v_pk_add_f32 v[100:101], v[100:101], v[174:175]
	ds_bpermute_b32 v175, v187, v101
	ds_bpermute_b32 v174, v187, v100
	s_waitcnt lgkmcnt(0)
	v_pk_add_f32 v[100:101], v[100:101], v[174:175]
	ds_bpermute_b32 v175, v188, v101
	ds_bpermute_b32 v174, v188, v100
	s_waitcnt lgkmcnt(0)
	v_pk_add_f32 v[100:101], v[100:101], v[174:175]
	ds_bpermute_b32 v175, v189, v101
	ds_bpermute_b32 v174, v189, v100
	s_waitcnt lgkmcnt(0)
	v_pk_add_f32 v[100:101], v[100:101], v[174:175]
	s_nop 0
	v_pk_fma_f32 v[100:101], v[100:101], s[6:7], v[140:141] op_sel_hi:[1,0,0]
	s_nop 0
	v_mul_f32_e32 v118, 0x4b800000, v101
	v_cmp_gt_f32_e64 s[0:1], s21, v101
	v_cmp_gt_f32_e32 vcc, s21, v100
	s_nop 0
	v_cndmask_b32_e64 v101, v101, v118, s[0:1]
	v_rsq_f32_e32 v101, v101
	s_nop 0
	v_mul_f32_e32 v118, 0x45800000, v101
	v_cndmask_b32_e64 v146, v101, v118, s[0:1]
	s_ashr_i32 s0, s2, 11
	s_mul_i32 s0, s0, 9
	s_ashr_i32 s1, s0, 31
	s_lshl_b64 s[0:1], s[0:1], 12
	s_add_u32 s5, s14, s0
	s_addc_u32 s13, s15, s1
	s_add_u32 s0, s5, 0x5000
	s_addc_u32 s1, s13, 0
	v_mul_f32_e32 v101, 0x4b800000, v100
	v_cndmask_b32_e32 v100, v100, v101, vcc
	v_rsq_f32_e32 v100, v100
	v_mov_b32_e32 v118, v121
	v_mul_f32_e32 v101, 0x45800000, v100
	v_cndmask_b32_e32 v130, v100, v101, vcc
	v_pk_mul_f32 v[196:197], v[230:231], v[200:201]
	v_pk_mul_f32 v[194:195], v[228:229], v[198:199]
	v_pk_fma_f32 v[174:175], v[92:93], v[196:197], v[50:51]
	v_pk_fma_f32 v[182:183], v[90:91], v[194:195], v[48:49]
	v_cvt_pk_bf16_f32 v49, v174, v175
	v_cvt_pk_bf16_f32 v48, v182, v183
	global_store_dwordx2 v[0:1], v[48:49], off nt
	v_pk_mul_f32 v[48:49], v[174:175], v[174:175]
	v_pk_mul_f32 v[50:51], v[182:183], v[182:183]
	s_nop 0
	v_pk_mov_b32 v[90:91], v[50:51], v[48:49] op_sel:[1,0]
	v_mov_b32_e32 v51, v49
	v_pk_add_f32 v[198:199], v[90:91], v[50:51]
	v_pk_mul_f32 v[48:49], v[120:121], v[94:95] op_sel_hi:[0,1]
	v_pk_mul_f32 v[50:51], v[120:121], v[96:97] op_sel_hi:[0,1]
	v_pk_fma_f32 v[94:95], v[50:51], v[196:197], v[62:63]
	v_pk_fma_f32 v[96:97], v[48:49], v[194:195], v[60:61]
	v_cvt_pk_bf16_f32 v49, v94, v95
	v_cvt_pk_bf16_f32 v48, v96, v97
	global_store_dwordx2 v[40:41], v[48:49], off nt
	v_pk_mul_f32 v[48:49], v[94:95], v[94:95]
	v_pk_mul_f32 v[50:51], v[96:97], v[96:97]
	s_nop 0
	v_pk_mov_b32 v[60:61], v[50:51], v[48:49] op_sel:[1,0]
	v_mov_b32_e32 v51, v49
	v_pk_add_f32 v[200:201], v[60:61], v[50:51]
	v_pk_mul_f32 v[48:49], v[146:147], v[176:177] op_sel_hi:[0,1]
	v_pk_mul_f32 v[50:51], v[146:147], v[98:99] op_sel_hi:[0,1]
	v_pk_fma_f32 v[98:99], v[196:197], v[50:51], v[74:75]
	v_pk_fma_f32 v[100:101], v[194:195], v[48:49], v[72:73]
	v_cvt_pk_bf16_f32 v49, v98, v99
	v_cvt_pk_bf16_f32 v48, v100, v101
	global_store_dwordx2 v[88:89], v[48:49], off nt
	v_pk_mul_f32 v[48:49], v[98:99], v[98:99]
	v_pk_mul_f32 v[50:51], v[100:101], v[100:101]
	s_nop 0
	v_pk_mov_b32 v[60:61], v[50:51], v[48:49] op_sel:[1,0]
	v_mov_b32_e32 v51, v49
	v_pk_add_f32 v[176:177], v[60:61], v[50:51]
	v_pk_mul_f32 v[48:49], v[130:131], v[178:179] op_sel_hi:[0,1]
	v_pk_mul_f32 v[50:51], v[130:131], v[180:181] op_sel_hi:[0,1]
	v_pk_fma_f32 v[90:91], v[196:197], v[50:51], v[78:79]
	v_pk_fma_f32 v[92:93], v[194:195], v[48:49], v[76:77]
	v_cvt_pk_bf16_f32 v49, v90, v91
	v_cvt_pk_bf16_f32 v48, v92, v93
	global_store_dwordx2 v[106:107], v[48:49], off nt
	v_pk_mul_f32 v[48:49], v[90:91], v[90:91]
	v_pk_mul_f32 v[50:51], v[92:93], v[92:93]
	s_nop 0
	v_pk_mov_b32 v[60:61], v[50:51], v[48:49] op_sel:[1,0]
	v_mov_b32_e32 v51, v49
	v_pk_add_f32 v[178:179], v[60:61], v[50:51]
	v_pk_mul_f32 v[48:49], v[232:233], v[236:237]
	v_mov_b32_e32 v60, v80
	v_mov_b32_e32 v61, v82
	v_mov_b32_e32 v82, v81
	v_pk_mul_f32 v[50:51], v[234:235], v[238:239]
	v_pk_mul_f32 v[60:61], v[128:129], v[60:61] op_sel_hi:[0,1]
	v_pk_mul_f32 v[62:63], v[128:129], v[82:83] op_sel_hi:[0,1]
	v_pk_fma_f32 v[76:77], v[62:63], v[50:51], v[42:43]
	v_pk_fma_f32 v[78:79], v[60:61], v[48:49], v[38:39]
	v_cvt_pk_bf16_f32 v39, v76, v77
	v_cvt_pk_bf16_f32 v38, v78, v79
	global_store_dwordx2 v[0:1], v[38:39], off offset:512 nt
	v_pk_mul_f32 v[38:39], v[78:79], v[78:79]
	v_pk_mul_f32 v[42:43], v[76:77], v[76:77]
	s_nop 0
	v_pk_mov_b32 v[60:61], v[38:39], v[42:43] op_sel:[1,0]
	v_mov_b32_e32 v39, v43
	v_mov_b32_e32 v42, v84
	v_mov_b32_e32 v43, v86
	v_mov_b32_e32 v86, v85
	v_pk_add_f32 v[38:39], v[60:61], v[38:39]
	v_pk_mul_f32 v[42:43], v[120:121], v[42:43] op_sel_hi:[0,1]
	v_pk_mul_f32 v[60:61], v[120:121], v[86:87] op_sel_hi:[0,1]
	v_pk_fma_f32 v[80:81], v[60:61], v[50:51], v[58:59]
	v_pk_fma_f32 v[82:83], v[42:43], v[48:49], v[56:57]
	v_cvt_pk_bf16_f32 v43, v80, v81
	v_cvt_pk_bf16_f32 v42, v82, v83
	global_store_dwordx2 v[40:41], v[42:43], off offset:512 nt
	v_pk_mul_f32 v[42:43], v[82:83], v[82:83]
	v_pk_mul_f32 v[56:57], v[80:81], v[80:81]
	s_nop 0
	v_pk_mov_b32 v[58:59], v[42:43], v[56:57] op_sel:[1,0]
	v_mov_b32_e32 v43, v57
	v_mov_b32_e32 v56, v162
	v_mov_b32_e32 v57, v164
	v_mov_b32_e32 v164, v163
	v_pk_add_f32 v[42:43], v[58:59], v[42:43]
	v_pk_mul_f32 v[56:57], v[146:147], v[56:57] op_sel_hi:[0,1]
	v_pk_mul_f32 v[58:59], v[146:147], v[164:165] op_sel_hi:[0,1]
	v_pk_fma_f32 v[84:85], v[58:59], v[50:51], v[68:69]
	v_pk_fma_f32 v[86:87], v[56:57], v[48:49], v[66:67]
	v_cvt_pk_bf16_f32 v57, v84, v85
	v_cvt_pk_bf16_f32 v56, v86, v87
	global_store_dwordx2 v[88:89], v[56:57], off offset:512 nt
	v_pk_mul_f32 v[56:57], v[86:87], v[86:87]
	v_pk_mul_f32 v[58:59], v[84:85], v[84:85]
	s_nop 0
	v_pk_mov_b32 v[60:61], v[56:57], v[58:59] op_sel:[1,0]
	v_mov_b32_e32 v57, v59
	v_pk_add_f32 v[162:163], v[60:61], v[56:57]
	v_mov_b32_e32 v56, v166
	v_mov_b32_e32 v57, v172
	v_mov_b32_e32 v172, v167
	v_pk_mul_f32 v[56:57], v[130:131], v[56:57] op_sel_hi:[0,1]
	v_pk_mul_f32 v[58:59], v[130:131], v[172:173] op_sel_hi:[0,1]
	v_pk_fma_f32 v[72:73], v[50:51], v[58:59], v[124:125]
	v_pk_fma_f32 v[74:75], v[48:49], v[56:57], v[122:123]
	v_cvt_pk_bf16_f32 v49, v72, v73
	v_cvt_pk_bf16_f32 v48, v74, v75
	global_store_dwordx2 v[106:107], v[48:49], off offset:512 nt
	v_pk_mul_f32 v[48:49], v[74:75], v[74:75]
	v_pk_mul_f32 v[50:51], v[72:73], v[72:73]
	s_nop 0
	v_pk_mov_b32 v[56:57], v[48:49], v[50:51] op_sel:[1,0]
	v_mov_b32_e32 v49, v51
	v_pk_add_f32 v[122:123], v[56:57], v[48:49]
	v_pk_mul_f32 v[50:51], v[242:243], v[246:247]
	v_pk_mul_f32 v[48:49], v[240:241], v[244:245]
	v_pk_mul_f32 v[56:57], v[128:129], v[132:133] op_sel_hi:[0,1]
	v_pk_mul_f32 v[58:59], v[128:129], v[134:135] op_sel_hi:[0,1]
	v_pk_fma_f32 v[60:61], v[58:59], v[50:51], v[36:37]
	v_pk_fma_f32 v[66:67], v[56:57], v[48:49], v[34:35]
	v_cvt_pk_bf16_f32 v35, v60, v61
	v_cvt_pk_bf16_f32 v34, v66, v67
	global_store_dwordx2 v[0:1], v[34:35], off offset:1024 nt
	v_pk_mul_f32 v[34:35], v[120:121], v[136:137] op_sel_hi:[0,1]
	v_pk_mul_f32 v[36:37], v[120:121], v[138:139] op_sel_hi:[0,1]
	v_pk_fma_f32 v[62:63], v[36:37], v[50:51], v[54:55]
	v_pk_fma_f32 v[68:69], v[34:35], v[48:49], v[52:53]
	v_cvt_pk_bf16_f32 v35, v62, v63
	v_cvt_pk_bf16_f32 v34, v68, v69
	global_store_dwordx2 v[40:41], v[34:35], off offset:1024 nt
	v_pk_mul_f32 v[34:35], v[146:147], v[154:155] op_sel_hi:[0,1]
	v_pk_mul_f32 v[36:37], v[146:147], v[156:157] op_sel_hi:[0,1]
	v_pk_fma_f32 v[64:65], v[36:37], v[50:51], v[64:65]
	v_pk_fma_f32 v[70:71], v[34:35], v[48:49], v[70:71]
	v_cvt_pk_bf16_f32 v35, v64, v65
	v_cvt_pk_bf16_f32 v34, v70, v71
	global_store_dwordx2 v[88:89], v[34:35], off offset:1024 nt
	v_pk_mul_f32 v[34:35], v[130:131], v[158:159] op_sel_hi:[0,1]
	v_pk_mul_f32 v[36:37], v[130:131], v[160:161] op_sel_hi:[0,1]
	v_pk_fma_f32 v[56:57], v[36:37], v[50:51], v[114:115]
	v_pk_fma_f32 v[58:59], v[34:35], v[48:49], v[112:113]
	v_cvt_pk_bf16_f32 v35, v56, v57
	v_cvt_pk_bf16_f32 v34, v58, v59
	global_store_dwordx2 v[106:107], v[34:35], off offset:1024 nt
	s_nop 0
	v_pk_mul_f32 v[50:51], v[214:215], v[218:219]
	v_pk_mul_f32 v[48:49], v[212:213], v[216:217]
	v_pk_mul_f32 v[34:35], v[128:129], v[118:119] op_sel_hi:[0,1]
	v_pk_mul_f32 v[36:37], v[128:129], v[116:117] op_sel_hi:[0,1]
	v_pk_fma_f32 v[32:33], v[36:37], v[50:51], v[32:33]
	v_pk_fma_f32 v[34:35], v[34:35], v[48:49], v[2:3]
	v_cvt_pk_bf16_f32 v3, v32, v33
	v_cvt_pk_bf16_f32 v2, v34, v35
	global_store_dwordx2 v[0:1], v[2:3], off offset:1536 nt
	v_mul_f32_e32 v2, v34, v34
	v_pk_add_f32 v[0:1], v[198:199], v[198:199] op_sel:[0,1] op_sel_hi:[1,0]
	v_mul_f32_e32 v36, v35, v35
	v_mov_b32_e32 v1, v2
	v_pk_add_f32 v[2:3], v[38:39], v[38:39] op_sel:[0,1] op_sel_hi:[1,0]
	v_mul_f32_e32 v37, v32, v32
	v_mov_b32_e32 v3, v36
	v_pk_add_f32 v[0:1], v[0:1], v[2:3]
	v_mul_f32_e32 v2, v67, v67
	v_pk_fma_f32 v[2:3], v[66:67], v[66:67], v[2:3] op_sel_hi:[1,1,0]
	v_mul_f32_e32 v36, v61, v61
	v_mul_f32_e32 v52, v33, v33
	v_mov_b32_e32 v3, v37
	v_pk_fma_f32 v[36:37], v[60:61], v[60:61], v[36:37] op_sel_hi:[1,1,0]
	v_mov_b32_e32 v128, v131
	v_mov_b32_e32 v37, v52
	v_pk_add_f32 v[2:3], v[2:3], v[36:37]
	v_pk_mul_f32 v[36:37], v[120:121], v[126:127] op_sel_hi:[0,1]
	v_pk_add_f32 v[0:1], v[0:1], v[2:3]
	v_pk_mul_f32 v[2:3], v[120:121], v[128:129] op_sel_hi:[0,1]
	v_pk_fma_f32 v[36:37], v[36:37], v[50:51], v[46:47]
	v_pk_fma_f32 v[38:39], v[2:3], v[48:49], v[44:45]
	v_cvt_pk_bf16_f32 v3, v36, v37
	v_cvt_pk_bf16_f32 v2, v38, v39
	global_store_dwordx2 v[40:41], v[2:3], off offset:1536 nt
	v_mul_f32_e32 v40, v38, v38
	v_pk_add_f32 v[2:3], v[200:201], v[200:201] op_sel:[0,1] op_sel_hi:[1,0]
	v_mul_f32_e32 v44, v39, v39
	v_mov_b32_e32 v3, v40
	v_pk_add_f32 v[40:41], v[42:43], v[42:43] op_sel:[0,1] op_sel_hi:[1,0]
	v_mul_f32_e32 v42, v63, v63
	v_mov_b32_e32 v41, v44
	v_pk_add_f32 v[2:3], v[2:3], v[40:41]
	v_mul_f32_e32 v40, v69, v69
	v_mul_f32_e32 v45, v36, v36
	v_mul_f32_e32 v46, v37, v37
	v_pk_fma_f32 v[40:41], v[68:69], v[68:69], v[40:41] op_sel_hi:[1,1,0]
	v_pk_fma_f32 v[42:43], v[62:63], v[62:63], v[42:43] op_sel_hi:[1,1,0]
	v_mov_b32_e32 v41, v45
	v_mov_b32_e32 v43, v46
	v_pk_add_f32 v[40:41], v[40:41], v[42:43]
	v_pk_mul_f32 v[42:43], v[146:147], v[144:145] op_sel_hi:[0,1]
	v_pk_add_f32 v[2:3], v[2:3], v[40:41]
	v_pk_mul_f32 v[40:41], v[146:147], v[142:143] op_sel_hi:[0,1]
	v_pk_fma_f32 v[40:41], v[40:41], v[50:51], v[104:105]
	v_pk_fma_f32 v[42:43], v[42:43], v[48:49], v[102:103]
	v_cvt_pk_bf16_f32 v45, v40, v41
	v_cvt_pk_bf16_f32 v44, v42, v43
	global_store_dwordx2 v[88:89], v[44:45], off offset:1536 nt
	v_mul_f32_e32 v46, v42, v42
	v_pk_add_f32 v[44:45], v[176:177], v[176:177] op_sel:[0,1] op_sel_hi:[1,0]
	v_mul_f32_e32 v52, v43, v43
	v_mov_b32_e32 v45, v46
	v_pk_add_f32 v[46:47], v[162:163], v[162:163] op_sel:[0,1] op_sel_hi:[1,0]
	v_mul_f32_e32 v53, v40, v40
	v_mov_b32_e32 v47, v52
	v_pk_add_f32 v[44:45], v[44:45], v[46:47]
	v_mul_f32_e32 v46, v71, v71
	v_pk_fma_f32 v[46:47], v[70:71], v[70:71], v[46:47] op_sel_hi:[1,1,0]
	v_mul_f32_e32 v52, v65, v65
	v_mul_f32_e32 v54, v41, v41
	v_mov_b32_e32 v47, v53
	v_pk_fma_f32 v[52:53], v[64:65], v[64:65], v[52:53] op_sel_hi:[1,1,0]
	s_nop 0
	v_mov_b32_e32 v53, v54
	v_pk_add_f32 v[46:47], v[46:47], v[52:53]
	s_nop 0
	v_pk_add_f32 v[52:53], v[44:45], v[46:47]
	v_pk_mul_f32 v[46:47], v[130:131], v[150:151] op_sel_hi:[0,1]
	v_pk_mul_f32 v[44:45], v[130:131], v[148:149] op_sel_hi:[0,1]
	v_pk_fma_f32 v[44:45], v[44:45], v[50:51], v[110:111]
	v_pk_fma_f32 v[46:47], v[46:47], v[48:49], v[108:109]
	v_cvt_pk_bf16_f32 v49, v44, v45
	v_cvt_pk_bf16_f32 v48, v46, v47
	global_store_dwordx2 v[106:107], v[48:49], off offset:1536 nt
	v_mul_f32_e32 v50, v46, v46
	v_pk_add_f32 v[48:49], v[178:179], v[178:179] op_sel:[0,1] op_sel_hi:[1,0]
	v_mul_f32_e32 v54, v47, v47
	v_mov_b32_e32 v49, v50
	v_pk_add_f32 v[50:51], v[122:123], v[122:123] op_sel:[0,1] op_sel_hi:[1,0]
	v_mul_f32_e32 v55, v44, v44
	v_mov_b32_e32 v51, v54
	v_pk_add_f32 v[48:49], v[48:49], v[50:51]
	v_mul_f32_e32 v50, v59, v59
	v_pk_fma_f32 v[50:51], v[58:59], v[58:59], v[50:51] op_sel_hi:[1,1,0]
	v_mul_f32_e32 v54, v57, v57
	v_mul_f32_e32 v88, v45, v45
	v_mov_b32_e32 v51, v55
	v_pk_fma_f32 v[54:55], v[56:57], v[56:57], v[54:55] op_sel_hi:[1,1,0]
	s_nop 0
	v_mov_b32_e32 v55, v88
	v_pk_add_f32 v[50:51], v[50:51], v[54:55]
	s_nop 0
	v_pk_add_f32 v[54:55], v[48:49], v[50:51]
	v_mov_b32_e32 v48, v2
	v_mov_b32_e32 v49, v0
	v_mov_b32_e32 v0, v3
	v_pk_add_f32 v[0:1], v[48:49], v[0:1]
	ds_bpermute_b32 v3, v184, v1
	ds_bpermute_b32 v2, v184, v0
	s_waitcnt lgkmcnt(0)
	v_pk_add_f32 v[0:1], v[0:1], v[2:3]
	ds_bpermute_b32 v3, v185, v1
	ds_bpermute_b32 v2, v185, v0
	s_waitcnt lgkmcnt(0)
	v_pk_add_f32 v[0:1], v[0:1], v[2:3]
	ds_bpermute_b32 v3, v186, v1
	ds_bpermute_b32 v2, v186, v0
	s_waitcnt lgkmcnt(0)
	v_pk_add_f32 v[0:1], v[0:1], v[2:3]
	ds_bpermute_b32 v3, v187, v1
	ds_bpermute_b32 v2, v187, v0
	s_waitcnt lgkmcnt(0)
	v_pk_add_f32 v[0:1], v[0:1], v[2:3]
	ds_bpermute_b32 v3, v188, v1
	ds_bpermute_b32 v2, v188, v0
	s_waitcnt lgkmcnt(0)
	v_pk_add_f32 v[0:1], v[0:1], v[2:3]
	ds_bpermute_b32 v3, v189, v1
	ds_bpermute_b32 v2, v189, v0
	s_waitcnt lgkmcnt(0)
	v_pk_add_f32 v[0:1], v[0:1], v[2:3]
	s_nop 0
	v_pk_fma_f32 v[0:1], v[0:1], s[6:7], v[140:141] op_sel_hi:[1,0,0]
	s_nop 0
	v_mul_f32_e32 v2, 0x4b800000, v1
	v_cmp_gt_f32_e64 s[0:1], s21, v1
	v_cmp_gt_f32_e32 vcc, s21, v0
	s_nop 0
	v_cndmask_b32_e64 v1, v1, v2, s[0:1]
	v_rsq_f32_e32 v1, v1
	s_nop 0
	v_mul_f32_e32 v2, 0x45800000, v1
	v_cndmask_b32_e64 v50, v1, v2, s[0:1]
	v_mul_f32_e32 v1, 0x4b800000, v0
	v_cndmask_b32_e32 v0, v0, v1, vcc
	v_rsq_f32_e32 v0, v0
	v_pk_mul_f32 v[78:79], v[78:79], v[50:51] op_sel_hi:[1,0]
	v_pk_mul_f32 v[76:77], v[76:77], v[50:51] op_sel_hi:[1,0]
	v_pk_mul_f32 v[66:67], v[66:67], v[50:51] op_sel_hi:[1,0]
	v_mul_f32_e32 v1, 0x45800000, v0
	v_cndmask_b32_e32 v48, v0, v1, vcc
	v_mov_b32_e32 v0, v54
	v_mov_b32_e32 v1, v52
	v_mov_b32_e32 v52, v55
	v_pk_add_f32 v[0:1], v[0:1], v[52:53]
	ds_bpermute_b32 v3, v184, v1
	ds_bpermute_b32 v2, v184, v0
	v_pk_mul_f32 v[96:97], v[96:97], v[48:49] op_sel_hi:[1,0]
	v_pk_mul_f32 v[94:95], v[94:95], v[48:49] op_sel_hi:[1,0]
	v_pk_mul_f32 v[60:61], v[60:61], v[50:51] op_sel_hi:[1,0]
	v_pk_mul_f32 v[62:63], v[62:63], v[48:49] op_sel_hi:[1,0]
	s_waitcnt lgkmcnt(0)
	v_pk_add_f32 v[0:1], v[0:1], v[2:3]
	ds_bpermute_b32 v3, v185, v1
	ds_bpermute_b32 v2, v185, v0
	v_pk_mul_f32 v[34:35], v[34:35], v[50:51] op_sel_hi:[1,0]
	v_pk_mul_f32 v[32:33], v[32:33], v[50:51] op_sel_hi:[1,0]
	s_waitcnt lgkmcnt(0)
	v_pk_add_f32 v[0:1], v[0:1], v[2:3]
	ds_bpermute_b32 v3, v186, v1
	ds_bpermute_b32 v2, v186, v0
	s_waitcnt lgkmcnt(0)
	v_pk_add_f32 v[0:1], v[0:1], v[2:3]
	ds_bpermute_b32 v3, v187, v1
	ds_bpermute_b32 v2, v187, v0
	s_waitcnt lgkmcnt(0)
	v_pk_add_f32 v[0:1], v[0:1], v[2:3]
	ds_bpermute_b32 v3, v188, v1
	ds_bpermute_b32 v2, v188, v0
	s_waitcnt lgkmcnt(0)
	v_pk_add_f32 v[0:1], v[0:1], v[2:3]
	ds_bpermute_b32 v3, v189, v1
	ds_bpermute_b32 v2, v189, v0
	s_waitcnt lgkmcnt(0)
	v_pk_add_f32 v[0:1], v[0:1], v[2:3]
	s_nop 0
	v_pk_fma_f32 v[0:1], v[0:1], s[6:7], v[140:141] op_sel_hi:[1,0,0]
	s_nop 0
	v_mul_f32_e32 v2, 0x4b800000, v1
	v_cmp_gt_f32_e64 s[0:1], s21, v1
	v_cmp_gt_f32_e32 vcc, s21, v0
	s_nop 0
	v_cndmask_b32_e64 v1, v1, v2, s[0:1]
	v_rsq_f32_e32 v1, v1
	s_nop 0
	v_mul_f32_e32 v2, 0x45800000, v1
	v_cndmask_b32_e64 v54, v1, v2, s[0:1]
	v_mul_f32_e32 v1, 0x4b800000, v0
	v_cndmask_b32_e32 v0, v0, v1, vcc
	v_rsq_f32_e32 v0, v0
	s_add_u32 s0, s5, 0x6000
	s_addc_u32 s1, s13, 0
	s_add_u32 s12, s5, 0x7000
	v_mul_f32_e32 v1, 0x45800000, v0
	v_cndmask_b32_e32 v52, v0, v1, vcc
	s_addc_u32 s13, s13, 0
	global_load_dwordx4 v[104:107], v[18:19], off
	global_load_dwordx4 v[108:111], v190, s[12:13]
	global_load_dwordx4 v[0:3], v190, s[0:1]
	v_pk_mul_f32 v[92:93], v[92:93], v[52:53] op_sel_hi:[1,0]
	v_pk_mul_f32 v[90:91], v[90:91], v[52:53] op_sel_hi:[1,0]
	s_or_b32 s16, s10, 0x1000
	v_pk_mul_f32 v[74:75], v[74:75], v[52:53] op_sel_hi:[1,0]
	v_pk_mul_f32 v[72:73], v[72:73], v[52:53] op_sel_hi:[1,0]
	v_pk_mul_f32 v[58:59], v[58:59], v[52:53] op_sel_hi:[1,0]
	v_pk_mul_f32 v[56:57], v[56:57], v[52:53] op_sel_hi:[1,0]
	s_add_i32 s2, s2, s3
	s_add_i32 s7, s7, s9
	s_add_i32 s18, s18, s19
	s_add_i32 s4, s4, s20
	s_waitcnt vmcnt(1)
	v_pk_add_f32 v[88:89], v[110:111], 1.0 op_sel_hi:[1,0]
	v_pk_add_f32 v[108:109], v[108:109], 1.0 op_sel_hi:[1,0]
	v_pk_mul_f32 v[102:103], v[106:107], v[88:89]
	v_pk_mul_f32 v[104:105], v[104:105], v[108:109]
	v_pk_mul_f32 v[88:89], v[182:183], v[50:51] op_sel_hi:[1,0]
	v_pk_mul_f32 v[106:107], v[174:175], v[50:51] op_sel_hi:[1,0]
	s_waitcnt vmcnt(0)
	v_pk_fma_f32 v[88:89], v[88:89], v[104:105], v[0:1]
	v_pk_fma_f32 v[94:95], v[94:95], v[102:103], v[2:3]
	v_pk_fma_f32 v[96:97], v[96:97], v[104:105], v[0:1]
	v_pk_fma_f32 v[108:109], v[106:107], v[102:103], v[2:3]
	v_cvt_pk_bf16_f32 v106, v88, v89
	v_lshl_add_u64 v[88:89], v[8:9], 0, s[10:11]
	v_cvt_pk_bf16_f32 v96, v96, v97
	v_cvt_pk_bf16_f32 v97, v94, v95
	global_store_dwordx2 v[88:89], v[96:97], off offset:2048
	v_pk_mul_f32 v[94:95], v[100:101], v[54:55] op_sel_hi:[1,0]
	v_pk_mul_f32 v[96:97], v[98:99], v[54:55] op_sel_hi:[1,0]
	v_pk_fma_f32 v[94:95], v[104:105], v[94:95], v[0:1]
	v_pk_fma_f32 v[96:97], v[102:103], v[96:97], v[2:3]
	v_pk_fma_f32 v[2:3], v[102:103], v[90:91], v[2:3]
	v_pk_fma_f32 v[0:1], v[104:105], v[92:93], v[0:1]
	s_or_b32 s10, s10, 0x1800
	v_cvt_pk_bf16_f32 v107, v108, v109
	v_cvt_pk_bf16_f32 v94, v94, v95
	v_cvt_pk_bf16_f32 v95, v96, v97
	v_lshl_add_u64 v[96:97], v[8:9], 0, s[16:17]
	v_cvt_pk_bf16_f32 v0, v0, v1
	v_cvt_pk_bf16_f32 v1, v2, v3
	v_lshl_add_u64 v[2:3], v[8:9], 0, s[10:11]
	global_store_dwordx2 v[88:89], v[106:107], off
	global_store_dwordx2 v[96:97], v[94:95], off
	global_store_dwordx2 v[2:3], v[0:1], off
	global_load_dwordx4 v[0:3], v[20:21], off
	s_nop 0
	global_load_dwordx4 v[90:93], v191, s[12:13]
	global_load_dwordx4 v[94:97], v191, s[0:1]
	s_cmpk_lt_i32 s2, 0x4000
	s_waitcnt vmcnt(1)
	v_pk_add_f32 v[92:93], v[92:93], 1.0 op_sel_hi:[1,0]
	v_pk_add_f32 v[90:91], v[90:91], 1.0 op_sel_hi:[1,0]
	v_pk_mul_f32 v[2:3], v[2:3], v[92:93]
	v_pk_mul_f32 v[0:1], v[0:1], v[90:91]
	s_waitcnt vmcnt(0)
	v_pk_fma_f32 v[76:77], v[76:77], v[2:3], v[96:97]
	v_pk_fma_f32 v[78:79], v[78:79], v[0:1], v[94:95]
	s_nop 0
	v_cvt_pk_bf16_f32 v78, v78, v79
	v_cvt_pk_bf16_f32 v79, v76, v77
	global_store_dwordx2 v[88:89], v[78:79], off offset:512
	v_pk_mul_f32 v[76:77], v[82:83], v[48:49] op_sel_hi:[1,0]
	v_pk_mul_f32 v[78:79], v[80:81], v[48:49] op_sel_hi:[1,0]
	v_pk_fma_f32 v[76:77], v[76:77], v[0:1], v[94:95]
	v_pk_fma_f32 v[78:79], v[78:79], v[2:3], v[96:97]
	v_cvt_pk_bf16_f32 v76, v76, v77
	v_cvt_pk_bf16_f32 v77, v78, v79
	global_store_dwordx2 v[88:89], v[76:77], off offset:2560
	v_pk_mul_f32 v[76:77], v[86:87], v[54:55] op_sel_hi:[1,0]
	v_pk_mul_f32 v[78:79], v[84:85], v[54:55] op_sel_hi:[1,0]
	v_pk_fma_f32 v[76:77], v[76:77], v[0:1], v[94:95]
	v_pk_fma_f32 v[78:79], v[78:79], v[2:3], v[96:97]
	v_pk_fma_f32 v[2:3], v[2:3], v[72:73], v[96:97]
	v_pk_fma_f32 v[0:1], v[0:1], v[74:75], v[94:95]
	v_cvt_pk_bf16_f32 v76, v76, v77
	v_cvt_pk_bf16_f32 v77, v78, v79
	v_lshl_add_u64 v[78:79], v[22:23], 0, s[16:17]
	v_cvt_pk_bf16_f32 v0, v0, v1
	v_cvt_pk_bf16_f32 v1, v2, v3
	v_lshl_add_u64 v[2:3], v[22:23], 0, s[10:11]
	global_store_dwordx2 v[78:79], v[76:77], off
	global_store_dwordx2 v[2:3], v[0:1], off
	global_load_dwordx4 v[0:3], v[24:25], off
	s_nop 0
	global_load_dwordx4 v[72:75], v192, s[12:13]
	global_load_dwordx4 v[76:79], v192, s[0:1]
	s_waitcnt vmcnt(1)
	v_pk_add_f32 v[74:75], v[74:75], 1.0 op_sel_hi:[1,0]
	v_pk_add_f32 v[72:73], v[72:73], 1.0 op_sel_hi:[1,0]
	v_pk_mul_f32 v[2:3], v[2:3], v[74:75]
	v_pk_mul_f32 v[0:1], v[0:1], v[72:73]
	s_waitcnt vmcnt(0)
	v_pk_fma_f32 v[60:61], v[60:61], v[2:3], v[78:79]
	v_pk_fma_f32 v[66:67], v[66:67], v[0:1], v[76:77]
	v_pk_fma_f32 v[62:63], v[62:63], v[2:3], v[78:79]
	v_cvt_pk_bf16_f32 v66, v66, v67
	v_cvt_pk_bf16_f32 v67, v60, v61
	v_pk_mul_f32 v[60:61], v[68:69], v[48:49] op_sel_hi:[1,0]
	global_store_dwordx2 v[88:89], v[66:67], off offset:1024
	v_pk_fma_f32 v[60:61], v[60:61], v[0:1], v[76:77]
	s_nop 0
	v_cvt_pk_bf16_f32 v60, v60, v61
	v_cvt_pk_bf16_f32 v61, v62, v63
	global_store_dwordx2 v[88:89], v[60:61], off offset:3072
	v_pk_mul_f32 v[60:61], v[70:71], v[54:55] op_sel_hi:[1,0]
	v_pk_mul_f32 v[62:63], v[64:65], v[54:55] op_sel_hi:[1,0]
	v_pk_fma_f32 v[60:61], v[60:61], v[0:1], v[76:77]
	v_pk_fma_f32 v[62:63], v[62:63], v[2:3], v[78:79]
	v_pk_fma_f32 v[2:3], v[56:57], v[2:3], v[78:79]
	v_pk_fma_f32 v[0:1], v[58:59], v[0:1], v[76:77]
	v_cvt_pk_bf16_f32 v60, v60, v61
	v_cvt_pk_bf16_f32 v61, v62, v63
	v_lshl_add_u64 v[62:63], v[26:27], 0, s[16:17]
	v_cvt_pk_bf16_f32 v0, v0, v1
	v_cvt_pk_bf16_f32 v1, v2, v3
	v_lshl_add_u64 v[2:3], v[26:27], 0, s[10:11]
	global_store_dwordx2 v[62:63], v[60:61], off
	global_store_dwordx2 v[2:3], v[0:1], off
	global_load_dwordx4 v[0:3], v[28:29], off
	s_nop 0
	global_load_dwordx4 v[56:59], v193, s[12:13]
	global_load_dwordx4 v[60:63], v193, s[0:1]
	s_waitcnt vmcnt(1)
	v_pk_add_f32 v[58:59], v[58:59], 1.0 op_sel_hi:[1,0]
	v_pk_add_f32 v[56:57], v[56:57], 1.0 op_sel_hi:[1,0]
	v_pk_mul_f32 v[2:3], v[2:3], v[58:59]
	v_pk_mul_f32 v[0:1], v[0:1], v[56:57]
	s_waitcnt vmcnt(0)
	v_pk_fma_f32 v[32:33], v[32:33], v[2:3], v[62:63]
	v_pk_fma_f32 v[34:35], v[34:35], v[0:1], v[60:61]
	s_nop 0
	v_cvt_pk_bf16_f32 v34, v34, v35
	v_cvt_pk_bf16_f32 v35, v32, v33
	global_store_dwordx2 v[88:89], v[34:35], off offset:1536
	v_pk_mul_f32 v[32:33], v[38:39], v[48:49] op_sel_hi:[1,0]
	v_pk_mul_f32 v[34:35], v[36:37], v[48:49] op_sel_hi:[1,0]
	v_pk_fma_f32 v[32:33], v[32:33], v[0:1], v[60:61]
	v_pk_fma_f32 v[34:35], v[34:35], v[2:3], v[62:63]
	v_cvt_pk_bf16_f32 v32, v32, v33
	v_cvt_pk_bf16_f32 v33, v34, v35
	global_store_dwordx2 v[88:89], v[32:33], off offset:3584
	v_pk_mul_f32 v[32:33], v[42:43], v[54:55] op_sel_hi:[1,0]
	v_pk_mul_f32 v[34:35], v[40:41], v[54:55] op_sel_hi:[1,0]
	v_pk_fma_f32 v[32:33], v[32:33], v[0:1], v[60:61]
	v_pk_fma_f32 v[34:35], v[34:35], v[2:3], v[62:63]
	v_cvt_pk_bf16_f32 v32, v32, v33
	v_cvt_pk_bf16_f32 v33, v34, v35
	v_lshl_add_u64 v[34:35], v[30:31], 0, s[16:17]
	global_store_dwordx2 v[34:35], v[32:33], off
	v_pk_mul_f32 v[32:33], v[46:47], v[52:53] op_sel_hi:[1,0]
	v_pk_mul_f32 v[34:35], v[44:45], v[52:53] op_sel_hi:[1,0]
	v_pk_fma_f32 v[0:1], v[32:33], v[0:1], v[60:61]
	v_pk_fma_f32 v[2:3], v[34:35], v[2:3], v[62:63]
	v_cvt_pk_bf16_f32 v0, v0, v1
	v_cvt_pk_bf16_f32 v1, v2, v3
	v_lshl_add_u64 v[2:3], v[30:31], 0, s[10:11]
	global_store_dwordx2 v[2:3], v[0:1], off
	s_cbranch_scc1 .LBB0_912

.LBB0_1103:
	s_ashr_i32 s7, s6, 31
	s_add_i32 s0, s6, 1
	s_ashr_i32 s16, s9, 11
	s_add_i32 s2, s6, 2
	s_add_i32 s4, s6, 3
	s_lshl_b64 s[10:11], s[6:7], 11
	s_ashr_i32 s1, s0, 31
	s_mul_i32 s16, s16, 9
	s_ashr_i32 s3, s2, 31
	s_ashr_i32 s5, s4, 31
	v_lshl_add_u64 v[22:23], v[4:5], 0, s[10:11]
	v_lshl_add_u64 v[24:25], v[6:7], 0, s[10:11]
	s_lshl_b64 s[10:11], s[0:1], 11
	s_ashr_i32 s17, s16, 31
	global_load_dwordx4 v[0:3], v[10:11], off
	s_lshl_b64 s[18:19], s[2:3], 11
	s_lshl_b64 s[20:21], s[4:5], 11
	global_load_dwordx2 v[36:37], v[24:25], off nt
	global_load_dwordx2 v[38:39], v[22:23], off nt
	global_load_dwordx2 v[40:41], v[22:23], off offset:512 nt
	global_load_dwordx2 v[42:43], v[22:23], off offset:1024 nt
	global_load_dwordx2 v[44:45], v[22:23], off offset:1536 nt
	global_load_dwordx2 v[46:47], v[22:23], off offset:2048 nt
	global_load_dwordx2 v[50:51], v[22:23], off offset:2560 nt
	global_load_dwordx2 v[76:77], v[24:25], off offset:512 nt
	global_load_dwordx2 v[48:49], v[24:25], off offset:1024 nt
	global_load_dwordx2 v[20:21], v[24:25], off offset:1536 nt
	v_lshl_add_u64 v[26:27], v[6:7], 0, s[10:11]
	global_load_dwordx2 v[52:53], v[22:23], off offset:3072 nt
	global_load_dwordx2 v[54:55], v[22:23], off offset:3584 nt
	s_lshl_b64 s[10:11], s[16:17], 12
	s_add_u32 s10, s88, s10
	v_add_co_u32_e32 v30, vcc, s14, v22
	s_addc_u32 s11, s89, s11
	v_lshl_add_u64 v[28:29], v[6:7], 0, s[18:19]
	v_addc_co_u32_e32 v31, vcc, 0, v23, vcc
	v_lshl_add_u64 v[32:33], v[6:7], 0, s[20:21]
	global_load_dwordx2 v[60:61], v[26:27], off nt
	global_load_dwordx2 v[62:63], v[28:29], off nt
	global_load_dwordx2 v[66:67], v[32:33], off nt
	global_load_dwordx2 v[78:79], v[26:27], off offset:512 nt
	global_load_dwordx2 v[56:57], v[26:27], off offset:1024 nt
	global_load_dwordx2 v[22:23], v[26:27], off offset:1536 nt
	global_load_dwordx2 v[84:85], v[30:31], off nt
	global_load_dwordx2 v[86:87], v[30:31], off offset:512 nt
	global_load_dwordx2 v[88:89], v[30:31], off offset:1024 nt
	global_load_dwordx2 v[90:91], v[30:31], off offset:1536 nt
	global_load_dwordx2 v[80:81], v[28:29], off offset:512 nt
	global_load_dwordx2 v[58:59], v[28:29], off offset:1024 nt
	global_load_dwordx2 v[24:25], v[28:29], off offset:1536 nt
	global_load_dwordx2 v[104:105], v[30:31], off offset:2048 nt
	global_load_dwordx2 v[106:107], v[30:31], off offset:2560 nt
	global_load_dwordx2 v[130:131], v[30:31], off offset:3072 nt
	global_load_dwordx2 v[132:133], v[30:31], off offset:3584 nt
	global_load_dwordx2 v[82:83], v[32:33], off offset:512 nt
	global_load_dwordx2 v[64:65], v[32:33], off offset:1024 nt
	global_load_dwordx2 v[26:27], v[32:33], off offset:1536 nt
	s_add_u32 s10, s10, 0x8000
	s_addc_u32 s11, s11, 0
	global_load_dwordx4 v[126:129], v122, s[10:11]
	s_lshl_b64 s[0:1], s[0:1], 12
	s_lshl_b64 s[4:5], s[4:5], 12
	v_lshl_add_u64 v[30:31], v[8:9], 0, s[0:1]
	s_lshl_b64 s[2:3], s[2:3], 12
	v_lshl_add_u64 v[34:35], v[8:9], 0, s[4:5]
	v_lshl_add_u64 v[32:33], v[8:9], 0, s[2:3]
	s_lshl_b64 s[16:17], s[6:7], 12
	v_lshl_add_u64 v[28:29], v[8:9], 0, s[16:17]
	s_add_i32 s6, s6, s13
	global_load_dwordx4 v[220:223], v123, s[10:11]
	global_load_dwordx4 v[224:227], v[12:13], off
	global_load_dwordx4 v[228:231], v124, s[10:11]
	global_load_dwordx4 v[232:235], v[14:15], off
	global_load_dwordx4 v[236:239], v125, s[10:11]
	global_load_dwordx4 v[240:243], v[16:17], off
	s_waitcnt vmcnt(26)
	v_lshlrev_b32_e32 v138, 16, v60
	v_and_b32_e32 v113, 0xffff0000, v38
	v_and_b32_e32 v115, 0xffff0000, v39
	v_and_b32_e32 v97, 0xffff0000, v41
	v_and_b32_e32 v96, 0xffff0000, v40
	v_and_b32_e32 v69, 0xffff0000, v42
	v_and_b32_e32 v135, 0xffff0000, v46
	v_and_b32_e32 v137, 0xffff0000, v47
	v_lshlrev_b32_e32 v108, 16, v36
	v_and_b32_e32 v109, 0xffff0000, v36
	v_and_b32_e32 v71, 0xffff0000, v52
	v_and_b32_e32 v75, 0xffff0000, v53
	v_lshlrev_b32_e32 v110, 16, v37
	v_and_b32_e32 v111, 0xffff0000, v37
	v_lshlrev_b32_e32 v112, 16, v38
	v_lshlrev_b32_e32 v114, 16, v39
	v_lshlrev_b32_e32 v93, 16, v41
	v_lshlrev_b32_e32 v92, 16, v40
	v_lshlrev_b32_e32 v68, 16, v42
	v_lshlrev_b32_e32 v72, 16, v43
	v_and_b32_e32 v73, 0xffff0000, v43
	v_lshlrev_b32_e32 v41, 16, v44
	v_and_b32_e32 v37, 0xffff0000, v44
	v_lshlrev_b32_e32 v38, 16, v45
	v_and_b32_e32 v39, 0xffff0000, v45
	v_lshlrev_b32_e32 v134, 16, v46
	v_lshlrev_b32_e32 v136, 16, v47
	v_lshlrev_b32_e32 v95, 16, v51
	v_lshlrev_b32_e32 v94, 16, v50
	v_and_b32_e32 v99, 0xffff0000, v51
	v_and_b32_e32 v98, 0xffff0000, v50
	v_lshlrev_b32_e32 v70, 16, v52
	v_lshlrev_b32_e32 v74, 16, v53
	v_lshlrev_b32_e32 v47, 16, v54
	v_and_b32_e32 v43, 0xffff0000, v54
	v_lshlrev_b32_e32 v44, 16, v55
	v_and_b32_e32 v45, 0xffff0000, v55
	v_and_b32_e32 v139, 0xffff0000, v60
	v_lshlrev_b32_e32 v140, 16, v61
	v_and_b32_e32 v141, 0xffff0000, v61
	s_waitcnt vmcnt(24)
	v_lshlrev_b32_e32 v146, 16, v66
	v_and_b32_e32 v147, 0xffff0000, v66
	v_lshlrev_b32_e32 v148, 16, v67
	v_and_b32_e32 v149, 0xffff0000, v67
	v_mul_f32_e32 v36, v115, v115
	v_pk_mul_f32 v[150:151], v[96:97], v[96:97]
	v_mul_f32_e32 v40, v113, v113
	v_mul_f32_e32 v42, v69, v69
	v_mul_f32_e32 v50, v137, v137
	v_mul_f32_e32 v54, v135, v135
	v_mul_f32_e32 v60, v71, v71
	v_mul_f32_e32 v66, v75, v75
	s_waitcnt vmcnt(20)
	v_and_b32_e32 v159, 0xffff0000, v84
	v_and_b32_e32 v161, 0xffff0000, v85
	s_waitcnt vmcnt(19)
	v_and_b32_e32 v103, 0xffff0000, v87
	v_and_b32_e32 v102, 0xffff0000, v86
	s_waitcnt vmcnt(17)
	v_lshlrev_b32_e32 v55, 16, v90
	v_and_b32_e32 v51, 0xffff0000, v90
	s_waitcnt vmcnt(13)
	v_and_b32_e32 v163, 0xffff0000, v104
	v_and_b32_e32 v165, 0xffff0000, v105
	s_waitcnt vmcnt(10)
	v_lshlrev_b32_e32 v67, 16, v132
	v_and_b32_e32 v61, 0xffff0000, v132
	v_lshlrev_b32_e32 v142, 16, v62
	v_and_b32_e32 v143, 0xffff0000, v62
	v_lshlrev_b32_e32 v144, 16, v63
	v_and_b32_e32 v145, 0xffff0000, v63
	v_mul_f32_e32 v156, v38, v38
	v_mul_f32_e32 v46, v73, v73
	v_pk_mul_f32 v[154:155], v[98:99], v[98:99]
	v_lshlrev_b32_e32 v158, 16, v84
	v_lshlrev_b32_e32 v160, 16, v85
	v_lshlrev_b32_e32 v101, 16, v87
	v_lshlrev_b32_e32 v100, 16, v86
	v_lshlrev_b32_e32 v84, 16, v88
	v_and_b32_e32 v85, 0xffff0000, v88
	v_lshlrev_b32_e32 v88, 16, v89
	v_and_b32_e32 v89, 0xffff0000, v89
	v_lshlrev_b32_e32 v52, 16, v91
	v_and_b32_e32 v53, 0xffff0000, v91
	v_lshlrev_b32_e32 v162, 16, v104
	v_lshlrev_b32_e32 v164, 16, v105
	v_lshlrev_b32_e32 v105, 16, v107
	v_lshlrev_b32_e32 v104, 16, v106
	v_and_b32_e32 v107, 0xffff0000, v107
	v_and_b32_e32 v106, 0xffff0000, v106
	v_lshlrev_b32_e32 v86, 16, v130
	v_and_b32_e32 v87, 0xffff0000, v130
	v_lshlrev_b32_e32 v90, 16, v131
	v_and_b32_e32 v91, 0xffff0000, v131
	v_lshlrev_b32_e32 v62, 16, v133
	v_and_b32_e32 v63, 0xffff0000, v133
	v_pk_fma_f32 v[130:131], v[114:115], v[114:115], v[36:37] op_sel_hi:[1,1,0]
	v_pk_fma_f32 v[132:133], v[92:93], v[92:93], v[150:151]
	v_pk_fma_f32 v[150:151], v[112:113], v[112:113], v[40:41] op_sel_hi:[1,1,0]
	v_pk_fma_f32 v[166:167], v[68:69], v[68:69], v[42:43] op_sel_hi:[1,1,0]
	v_pk_fma_f32 v[170:171], v[136:137], v[136:137], v[50:51] op_sel_hi:[1,1,0]
	v_pk_fma_f32 v[172:173], v[134:135], v[134:135], v[54:55] op_sel_hi:[1,1,0]
	v_pk_fma_f32 v[174:175], v[70:71], v[70:71], v[60:61] op_sel_hi:[1,1,0]
	v_pk_fma_f32 v[176:177], v[74:75], v[74:75], v[66:67] op_sel_hi:[1,1,0]
	v_mul_f32_e32 v36, v161, v161
	v_pk_mul_f32 v[178:179], v[102:103], v[102:103]
	v_mul_f32_e32 v42, v159, v159
	v_mul_f32_e32 v60, v165, v165
	v_mul_f32_e32 v66, v163, v163
	v_mul_f32_e32 v186, v39, v39
	v_mov_b32_e32 v153, v41
	v_mul_f32_e32 v187, v44, v44
	v_mul_f32_e32 v188, v45, v45
	v_mov_b32_e32 v157, v47
	v_pk_fma_f32 v[168:169], v[72:73], v[72:73], v[46:47] op_sel_hi:[1,1,0]
	v_pk_fma_f32 v[154:155], v[94:95], v[94:95], v[154:155]
	v_mov_b32_e32 v181, v55
	v_mul_f32_e32 v54, v89, v89
	v_pk_mul_f32 v[182:183], v[106:107], v[106:107]
	v_mov_b32_e32 v185, v67
	v_mul_f32_e32 v180, v87, v87
	v_mul_f32_e32 v184, v91, v91
	v_mov_b32_e32 v40, v150
	v_mov_b32_e32 v152, v130
	v_pk_add_f32 v[130:131], v[150:151], v[130:131]
	v_mov_b32_e32 v167, v156
	v_mov_b32_e32 v46, v172
	v_mov_b32_e32 v156, v170
	v_pk_add_f32 v[150:151], v[172:173], v[170:171]
	v_pk_fma_f32 v[170:171], v[160:161], v[160:161], v[36:37] op_sel_hi:[1,1,0]
	v_pk_fma_f32 v[172:173], v[100:101], v[100:101], v[178:179]
	v_pk_fma_f32 v[178:179], v[158:159], v[158:159], v[42:43] op_sel_hi:[1,1,0]
	v_pk_fma_f32 v[190:191], v[164:165], v[164:165], v[60:61] op_sel_hi:[1,1,0]
	v_pk_fma_f32 v[192:193], v[162:163], v[162:163], v[66:67] op_sel_hi:[1,1,0]
	v_mul_f32_e32 v198, v37, v37
	v_mul_f32_e32 v199, v43, v43
	v_mul_f32_e32 v50, v85, v85
	v_pk_add_f32 v[132:133], v[132:133], v[132:133] op_sel:[0,1] op_sel_hi:[1,0]
	v_mov_b32_e32 v169, v186
	v_pk_add_f32 v[154:155], v[154:155], v[154:155] op_sel:[0,1] op_sel_hi:[1,0]
	v_mov_b32_e32 v175, v187
	v_mov_b32_e32 v177, v188
	v_pk_fma_f32 v[188:189], v[88:89], v[88:89], v[54:55] op_sel_hi:[1,1,0]
	v_pk_fma_f32 v[182:183], v[104:105], v[104:105], v[182:183]
	v_pk_fma_f32 v[194:195], v[86:87], v[86:87], v[180:181] op_sel_hi:[1,1,0]
	v_pk_fma_f32 v[196:197], v[90:91], v[90:91], v[184:185] op_sel_hi:[1,1,0]
	v_pk_mul_f32 v[152:153], v[40:41], v[152:153]
	v_pk_mul_f32 v[156:157], v[46:47], v[156:157]
	v_mov_b32_e32 v54, v178
	v_mov_b32_e32 v180, v170
	v_mov_b32_e32 v66, v192
	v_mov_b32_e32 v184, v190
	v_mul_f32_e32 v200, v51, v51
	v_mul_f32_e32 v201, v52, v52
	v_mul_f32_e32 v202, v53, v53
	v_mul_f32_e32 v203, v61, v61
	v_mul_f32_e32 v204, v62, v62
	v_mul_f32_e32 v205, v63, v63
	v_pk_fma_f32 v[186:187], v[84:85], v[84:85], v[50:51] op_sel_hi:[1,1,0]
	v_mov_b32_e32 v133, v198
	v_pk_add_f32 v[166:167], v[166:167], v[168:169]
	v_mov_b32_e32 v155, v199
	v_pk_add_f32 v[168:169], v[174:175], v[176:177]
	v_pk_add_f32 v[170:171], v[178:179], v[170:171]
	v_pk_add_f32 v[172:173], v[172:173], v[172:173] op_sel:[0,1] op_sel_hi:[1,0]
	v_pk_add_f32 v[174:175], v[192:193], v[190:191]
	v_pk_add_f32 v[176:177], v[182:183], v[182:183] op_sel:[0,1] op_sel_hi:[1,0]
	v_mov_b32_e32 v131, v153
	v_mov_b32_e32 v151, v157
	v_pk_mul_f32 v[152:153], v[54:55], v[180:181]
	v_pk_mul_f32 v[178:179], v[66:67], v[184:185]
	v_mov_b32_e32 v187, v201
	v_mov_b32_e32 v189, v202
	v_mov_b32_e32 v195, v204
	v_mov_b32_e32 v197, v205
	v_mov_b32_e32 v173, v200
	v_mov_b32_e32 v177, v203
	s_waitcnt vmcnt(0)
	v_pk_mul_f32 v[128:129], v[128:129], v[2:3]
	v_pk_mul_f32 v[126:127], v[126:127], v[0:1]
	v_pk_add_f32 v[0:1], v[130:131], v[132:133]
	v_pk_add_f32 v[2:3], v[150:151], v[154:155]
	v_mov_b32_e32 v171, v153
	v_mov_b32_e32 v175, v179
	v_pk_add_f32 v[156:157], v[186:187], v[188:189]
	v_pk_add_f32 v[180:181], v[194:195], v[196:197]
	v_pk_add_f32 v[0:1], v[0:1], v[166:167]
	v_pk_add_f32 v[2:3], v[2:3], v[168:169]
	v_pk_add_f32 v[130:131], v[170:171], v[172:173]
	v_pk_add_f32 v[132:133], v[174:175], v[176:177]
	v_mov_b32_e32 v150, v2
	v_mov_b32_e32 v151, v0
	v_mov_b32_e32 v0, v3
	v_pk_add_f32 v[2:3], v[130:131], v[156:157]
	v_pk_add_f32 v[130:131], v[132:133], v[180:181]
	v_pk_add_f32 v[0:1], v[150:151], v[0:1]
	v_mov_b32_e32 v132, v130
	v_mov_b32_e32 v133, v2
	v_mov_b32_e32 v2, v131
	ds_bpermute_b32 v131, v116, v1
	ds_bpermute_b32 v130, v116, v0
	v_pk_add_f32 v[2:3], v[132:133], v[2:3]
	ds_bpermute_b32 v133, v116, v3
	ds_bpermute_b32 v132, v116, v2
	v_mov_b32_e32 v50, v55
	s_waitcnt lgkmcnt(2)
	v_pk_add_f32 v[0:1], v[0:1], v[130:131]
	ds_bpermute_b32 v131, v117, v1
	ds_bpermute_b32 v130, v117, v0
	s_waitcnt lgkmcnt(2)
	v_pk_add_f32 v[2:3], v[2:3], v[132:133]
	ds_bpermute_b32 v133, v117, v3
	ds_bpermute_b32 v132, v117, v2
	v_mov_b32_e32 v60, v67
	s_waitcnt lgkmcnt(2)
	v_pk_add_f32 v[0:1], v[0:1], v[130:131]
	ds_bpermute_b32 v131, v118, v1
	ds_bpermute_b32 v130, v118, v0
	s_waitcnt lgkmcnt(2)
	v_pk_add_f32 v[2:3], v[2:3], v[132:133]
	ds_bpermute_b32 v133, v118, v3
	ds_bpermute_b32 v132, v118, v2
	s_waitcnt lgkmcnt(2)
	v_pk_add_f32 v[0:1], v[0:1], v[130:131]
	ds_bpermute_b32 v131, v119, v1
	ds_bpermute_b32 v130, v119, v0
	s_waitcnt lgkmcnt(2)
	v_pk_add_f32 v[2:3], v[2:3], v[132:133]
	ds_bpermute_b32 v133, v119, v3
	ds_bpermute_b32 v132, v119, v2
	s_waitcnt lgkmcnt(2)
	v_pk_add_f32 v[0:1], v[0:1], v[130:131]
	ds_bpermute_b32 v131, v120, v1
	ds_bpermute_b32 v130, v120, v0
	s_waitcnt lgkmcnt(2)
	v_pk_add_f32 v[2:3], v[2:3], v[132:133]
	ds_bpermute_b32 v133, v120, v3
	ds_bpermute_b32 v132, v120, v2
	s_waitcnt lgkmcnt(2)
	v_pk_add_f32 v[0:1], v[0:1], v[130:131]
	ds_bpermute_b32 v131, v121, v1
	ds_bpermute_b32 v130, v121, v0
	s_waitcnt lgkmcnt(2)
	v_pk_add_f32 v[2:3], v[2:3], v[132:133]
	ds_bpermute_b32 v133, v121, v3
	ds_bpermute_b32 v132, v121, v2
	s_waitcnt lgkmcnt(2)
	v_pk_add_f32 v[0:1], v[0:1], v[130:131]
	s_nop 0
	v_pk_fma_f32 v[0:1], v[0:1], s[8:9], v[18:19] op_sel_hi:[1,0,0]
	s_waitcnt lgkmcnt(0)
	v_pk_add_f32 v[2:3], v[2:3], v[132:133]
	v_mul_f32_e32 v36, 0x4b800000, v1
	v_mul_f32_e32 v40, 0x4b800000, v0
	v_cmp_gt_f32_e32 vcc, s15, v0
	v_pk_fma_f32 v[2:3], v[2:3], s[8:9], v[18:19] op_sel_hi:[1,0,0]
	v_cmp_gt_f32_e64 s[0:1], s15, v1
	v_cndmask_b32_e32 v0, v0, v40, vcc
	v_cmp_gt_f32_e64 s[4:5], s15, v3
	v_cndmask_b32_e64 v1, v1, v36, s[0:1]
	v_mul_f32_e32 v36, 0x4b800000, v3
	v_mul_f32_e32 v40, 0x4b800000, v2
	v_cmp_gt_f32_e64 s[2:3], s15, v2
	v_rsq_f32_e32 v1, v1
	v_rsq_f32_e32 v0, v0
	v_cndmask_b32_e64 v3, v3, v36, s[4:5]
	v_cndmask_b32_e64 v2, v2, v40, s[2:3]
	v_rsq_f32_e32 v3, v3
	v_rsq_f32_e32 v2, v2
	v_mul_f32_e32 v36, 0x45800000, v1
	v_mul_f32_e32 v40, 0x45800000, v0
	v_cndmask_b32_e64 v1, v1, v36, s[0:1]
	v_cndmask_b32_e32 v0, v0, v40, vcc
	v_mul_f32_e32 v36, 0x45800000, v3
	v_mul_f32_e32 v42, 0x45800000, v2
	v_mul_f32_e32 v40, 0.5, v1
	v_mul_f32_e32 v0, 0.5, v0
	v_cndmask_b32_e64 v1, v3, v36, s[4:5]
	v_cndmask_b32_e64 v2, v2, v42, s[2:3]
	v_mul_f32_e32 v46, 0.5, v1
	v_pk_mul_f32 v[112:113], v[40:41], v[112:113] op_sel_hi:[0,1]
	v_pk_mul_f32 v[114:115], v[40:41], v[114:115] op_sel_hi:[0,1]
	v_pk_mul_f32 v[130:131], v[0:1], v[134:135] op_sel_hi:[0,1]
	v_pk_mul_f32 v[132:133], v[0:1], v[136:137] op_sel_hi:[0,1]
	v_mul_f32_e32 v2, 0.5, v2
	v_pk_fma_f32 v[110:111], v[114:115], v[128:129], v[110:111]
	v_pk_fma_f32 v[108:109], v[112:113], v[126:127], v[108:109]
	v_pk_fma_f32 v[114:115], v[132:133], v[128:129], v[140:141]
	v_pk_fma_f32 v[112:113], v[130:131], v[126:127], v[138:139]
	v_pk_mul_f32 v[130:131], v[46:47], v[158:159] op_sel_hi:[0,1]
	v_pk_mul_f32 v[132:133], v[46:47], v[160:161] op_sel_hi:[0,1]
	v_pk_mul_f32 v[134:135], v[2:3], v[162:163] op_sel_hi:[0,1]
	v_pk_mul_f32 v[136:137], v[2:3], v[164:165] op_sel_hi:[0,1]
	global_store_dwordx4 v[28:29], v[108:111], off nt
	global_store_dwordx4 v[30:31], v[112:115], off nt
	v_lshlrev_b32_e32 v138, 16, v82
	v_pk_fma_f32 v[110:111], v[128:129], v[132:133], v[144:145]
	v_pk_fma_f32 v[108:109], v[126:127], v[130:131], v[142:143]
	v_pk_fma_f32 v[114:115], v[128:129], v[136:137], v[148:149]
	v_pk_fma_f32 v[112:113], v[126:127], v[134:135], v[146:147]
	global_store_dwordx4 v[32:33], v[108:111], off nt
	global_store_dwordx4 v[34:35], v[112:115], off nt
	s_nop 0
	v_lshlrev_b32_e32 v126, 16, v76
	v_and_b32_e32 v127, 0xffff0000, v76
	v_lshlrev_b32_e32 v128, 16, v77
	v_and_b32_e32 v129, 0xffff0000, v77
	v_mov_b32_e32 v76, v93
	v_mov_b32_e32 v77, v97
	v_mov_b32_e32 v93, v96
	v_lshlrev_b32_e32 v130, 16, v78
	v_and_b32_e32 v131, 0xffff0000, v78
	v_lshlrev_b32_e32 v132, 16, v79
	v_and_b32_e32 v133, 0xffff0000, v79
	v_lshlrev_b32_e32 v134, 16, v80
	v_and_b32_e32 v135, 0xffff0000, v80
	v_lshlrev_b32_e32 v136, 16, v81
	v_and_b32_e32 v137, 0xffff0000, v81
	v_and_b32_e32 v139, 0xffff0000, v82
	v_lshlrev_b32_e32 v140, 16, v83
	v_and_b32_e32 v141, 0xffff0000, v83
	v_mov_b32_e32 v78, v95
	v_mov_b32_e32 v79, v99
	v_mov_b32_e32 v95, v98
	v_mov_b32_e32 v80, v101
	v_mov_b32_e32 v81, v103
	v_mov_b32_e32 v82, v105
	v_mov_b32_e32 v83, v107
	v_mov_b32_e32 v101, v102
	v_mov_b32_e32 v105, v106
	v_pk_mul_f32 v[96:97], v[40:41], v[76:77] op_sel_hi:[0,1]
	v_pk_mul_f32 v[76:77], v[40:41], v[92:93] op_sel_hi:[0,1]
	v_pk_mul_f32 v[92:93], v[0:1], v[78:79] op_sel_hi:[0,1]
	v_pk_mul_f32 v[94:95], v[0:1], v[94:95] op_sel_hi:[0,1]
	v_pk_mul_f32 v[98:99], v[46:47], v[80:81] op_sel_hi:[0,1]
	v_pk_mul_f32 v[100:101], v[46:47], v[100:101] op_sel_hi:[0,1]
	v_pk_mul_f32 v[102:103], v[2:3], v[82:83] op_sel_hi:[0,1]
	v_pk_mul_f32 v[104:105], v[2:3], v[104:105] op_sel_hi:[0,1]
	v_pk_mul_f32 v[84:85], v[46:47], v[84:85] op_sel_hi:[0,1]
	v_pk_mul_f32 v[86:87], v[2:3], v[86:87] op_sel_hi:[0,1]
	v_mov_b32_e32 v36, v41
	v_mov_b32_e32 v42, v47
	s_add_i32 s9, s9, s12
	s_cmpk_lt_i32 s9, 0x4000
	v_pk_mul_f32 v[106:107], v[222:223], v[226:227]
	v_pk_mul_f32 v[108:109], v[220:221], v[224:225]
	v_pk_fma_f32 v[78:79], v[96:97], v[106:107], v[128:129]
	v_pk_fma_f32 v[76:77], v[76:77], v[108:109], v[126:127]
	v_pk_fma_f32 v[80:81], v[94:95], v[108:109], v[130:131]
	v_pk_fma_f32 v[82:83], v[92:93], v[106:107], v[132:133]
	v_pk_fma_f32 v[92:93], v[100:101], v[108:109], v[134:135]
	v_pk_fma_f32 v[94:95], v[98:99], v[106:107], v[136:137]
	v_pk_fma_f32 v[96:97], v[108:109], v[104:105], v[138:139]
	v_pk_fma_f32 v[98:99], v[106:107], v[102:103], v[140:141]
	global_store_dwordx4 v[28:29], v[76:79], off offset:1024 nt
	global_store_dwordx4 v[30:31], v[80:83], off offset:1024 nt
	global_store_dwordx4 v[32:33], v[92:95], off offset:1024 nt
	global_store_dwordx4 v[34:35], v[96:99], off offset:1024 nt
	s_nop 0
	v_lshlrev_b32_e32 v92, 16, v48
	v_and_b32_e32 v93, 0xffff0000, v48
	v_lshlrev_b32_e32 v48, 16, v49
	v_and_b32_e32 v49, 0xffff0000, v49
	v_lshlrev_b32_e32 v94, 16, v56
	v_and_b32_e32 v95, 0xffff0000, v56
	v_lshlrev_b32_e32 v96, 16, v57
	v_and_b32_e32 v97, 0xffff0000, v57
	v_lshlrev_b32_e32 v98, 16, v58
	v_and_b32_e32 v99, 0xffff0000, v58
	v_lshlrev_b32_e32 v100, 16, v59
	v_and_b32_e32 v101, 0xffff0000, v59
	v_pk_mul_f32 v[58:59], v[40:41], v[72:73] op_sel_hi:[0,1]
	v_pk_mul_f32 v[56:57], v[40:41], v[68:69] op_sel_hi:[0,1]
	v_lshlrev_b32_e32 v102, 16, v64
	v_and_b32_e32 v103, 0xffff0000, v64
	v_lshlrev_b32_e32 v64, 16, v65
	v_and_b32_e32 v65, 0xffff0000, v65
	v_pk_mul_f32 v[72:73], v[0:1], v[74:75] op_sel_hi:[0,1]
	v_pk_mul_f32 v[68:69], v[0:1], v[70:71] op_sel_hi:[0,1]
	v_pk_mul_f32 v[74:75], v[46:47], v[88:89] op_sel_hi:[0,1]
	v_pk_mul_f32 v[88:89], v[2:3], v[90:91] op_sel_hi:[0,1]
	v_pk_mul_f32 v[78:79], v[230:231], v[234:235]
	v_pk_mul_f32 v[76:77], v[228:229], v[232:233]
	v_pk_fma_f32 v[58:59], v[58:59], v[78:79], v[48:49]
	v_pk_fma_f32 v[56:57], v[56:57], v[76:77], v[92:93]
	v_pk_fma_f32 v[68:69], v[68:69], v[76:77], v[94:95]
	v_pk_fma_f32 v[70:71], v[72:73], v[78:79], v[96:97]
	v_pk_fma_f32 v[72:73], v[84:85], v[76:77], v[98:99]
	v_pk_fma_f32 v[74:75], v[74:75], v[78:79], v[100:101]
	v_pk_fma_f32 v[76:77], v[86:87], v[76:77], v[102:103]
	v_pk_fma_f32 v[78:79], v[88:89], v[78:79], v[64:65]
	global_store_dwordx4 v[28:29], v[56:59], off offset:2048 nt
	global_store_dwordx4 v[30:31], v[68:71], off offset:2048 nt
	global_store_dwordx4 v[32:33], v[72:75], off offset:2048 nt
	global_store_dwordx4 v[34:35], v[76:79], off offset:2048 nt
	s_nop 0
	v_lshlrev_b32_e32 v48, 16, v20
	v_and_b32_e32 v49, 0xffff0000, v20
	v_lshlrev_b32_e32 v20, 16, v21
	v_and_b32_e32 v21, 0xffff0000, v21
	v_lshlrev_b32_e32 v72, 16, v24
	v_and_b32_e32 v73, 0xffff0000, v24
	v_lshlrev_b32_e32 v74, 16, v25
	v_and_b32_e32 v75, 0xffff0000, v25
	v_lshlrev_b32_e32 v76, 16, v26
	v_and_b32_e32 v77, 0xffff0000, v26
	v_lshlrev_b32_e32 v78, 16, v27
	v_and_b32_e32 v79, 0xffff0000, v27
	v_pk_mul_f32 v[24:25], v[40:41], v[38:39] op_sel_hi:[0,1]
	v_pk_mul_f32 v[26:27], v[40:41], v[36:37] op_sel_hi:[0,1]
	v_pk_mul_f32 v[38:39], v[0:1], v[42:43] op_sel_hi:[0,1]
	v_pk_mul_f32 v[40:41], v[46:47], v[52:53] op_sel_hi:[0,1]
	v_pk_mul_f32 v[42:43], v[46:47], v[50:51] op_sel_hi:[0,1]
	v_lshlrev_b32_e32 v64, 16, v22
	v_and_b32_e32 v65, 0xffff0000, v22
	v_lshlrev_b32_e32 v22, 16, v23
	v_and_b32_e32 v23, 0xffff0000, v23
	v_pk_mul_f32 v[36:37], v[0:1], v[44:45] op_sel_hi:[0,1]
	v_pk_mul_f32 v[44:45], v[2:3], v[62:63] op_sel_hi:[0,1]
	v_pk_mul_f32 v[46:47], v[2:3], v[60:61] op_sel_hi:[0,1]
	v_pk_mul_f32 v[50:51], v[238:239], v[242:243]
	v_pk_mul_f32 v[52:53], v[236:237], v[240:241]
	v_pk_fma_f32 v[2:3], v[24:25], v[50:51], v[20:21]
	v_pk_fma_f32 v[0:1], v[26:27], v[52:53], v[48:49]
	v_pk_fma_f32 v[20:21], v[38:39], v[52:53], v[64:65]
	v_pk_fma_f32 v[22:23], v[36:37], v[50:51], v[22:23]
	v_pk_fma_f32 v[24:25], v[42:43], v[52:53], v[72:73]
	v_pk_fma_f32 v[26:27], v[40:41], v[50:51], v[74:75]
	v_pk_fma_f32 v[36:37], v[46:47], v[52:53], v[76:77]
	v_pk_fma_f32 v[38:39], v[44:45], v[50:51], v[78:79]
	global_store_dwordx4 v[28:29], v[0:3], off offset:3072 nt
	global_store_dwordx4 v[30:31], v[20:23], off offset:3072 nt
	global_store_dwordx4 v[32:33], v[24:27], off offset:3072 nt
	global_store_dwordx4 v[34:35], v[36:39], off offset:3072 nt
	s_cbranch_scc1 .LBB0_1103
